# baseline (speedup 1.0000x reference)
.Lglds2_2829:
	ds_read_b128 v[152:155], v112 offset:16384
	ds_read_b128 v[156:159], v110
	ds_read_b128 v[160:163], v112 offset:18432
	ds_read_b128 v[164:167], v112 offset:20480
	ds_read_b128 v[168:171], v113 offset:16384
	ds_read_b128 v[172:175], v110 offset:2048
	ds_read_b128 v[208:211], v110 offset:4096
	ds_read_b128 v[212:215], v111
	ds_read_b128 v[216:219], v116 offset:16384
	ds_read_b128 v[220:223], v114
	ds_read_b128 v[224:227], v116 offset:18432
	ds_read_b128 v[228:231], v116 offset:20480
	ds_read_b128 v[232:235], v117 offset:16384
	ds_read_b128 v[236:239], v114 offset:2048
	ds_read_b128 v[240:243], v114 offset:4096
	ds_read_b128 v[244:247], v115
	s_setprio 1
	s_waitcnt lgkmcnt(14)
	v_mfma_f32_16x16x32_bf16 v[94:97], v[152:155], v[156:159], v[94:97]
	s_waitcnt lgkmcnt(13)
	v_mfma_f32_16x16x32_bf16 v[90:93], v[160:163], v[156:159], v[90:93]
	s_waitcnt lgkmcnt(12)
	v_mfma_f32_16x16x32_bf16 v[86:89], v[164:167], v[156:159], v[86:89]
	s_waitcnt lgkmcnt(11)
	v_mfma_f32_16x16x32_bf16 v[82:85], v[168:171], v[156:159], v[82:85]
	s_waitcnt lgkmcnt(10)
	v_mfma_f32_16x16x32_bf16 v[78:81], v[152:155], v[172:175], v[78:81]
	v_mfma_f32_16x16x32_bf16 v[62:65], v[160:163], v[172:175], v[62:65]
	v_mfma_f32_16x16x32_bf16 v[46:49], v[164:167], v[172:175], v[46:49]
	v_mfma_f32_16x16x32_bf16 v[26:29], v[168:171], v[172:175], v[26:29]
	s_waitcnt lgkmcnt(9)
	v_mfma_f32_16x16x32_bf16 v[38:41], v[152:155], v[208:211], v[38:41]
	v_mfma_f32_16x16x32_bf16 v[30:33], v[160:163], v[208:211], v[30:33]
	v_mfma_f32_16x16x32_bf16 v[22:25], v[164:167], v[208:211], v[22:25]
	v_mfma_f32_16x16x32_bf16 v[18:21], v[168:171], v[208:211], v[18:21]
	s_waitcnt lgkmcnt(8)
	v_mfma_f32_16x16x32_bf16 v[14:17], v[152:155], v[212:215], v[14:17]
	v_mfma_f32_16x16x32_bf16 v[10:13], v[160:163], v[212:215], v[10:13]
	v_mfma_f32_16x16x32_bf16 v[6:9], v[164:167], v[212:215], v[6:9]
	v_mfma_f32_16x16x32_bf16 v[2:5], v[168:171], v[212:215], v[2:5]
	s_setprio 0
	s_waitcnt lgkmcnt(0)
	s_barrier
	s_add_i32 s0, s5, 0x80
	s_min_u32 s0, s0, 0x3c0
	s_lshl_b32 s0, s0, 1
	s_setprio 1
	v_mfma_f32_16x16x32_bf16 v[94:97], v[216:219], v[220:223], v[94:97]
	s_add_u32 m0, s6, 0x0
	v_lshl_add_u64 v[204:205], v[188:189], 0, s[0:1]
	global_load_lds_dwordx4 v[204:205], off
	v_mfma_f32_16x16x32_bf16 v[90:93], v[224:227], v[220:223], v[90:93]
	v_mfma_f32_16x16x32_bf16 v[86:89], v[228:231], v[220:223], v[86:89]
	s_add_u32 m0, s6, 0x1000
	v_lshl_add_u64 v[206:207], v[190:191], 0, s[0:1]
	global_load_lds_dwordx4 v[206:207], off
	v_mfma_f32_16x16x32_bf16 v[82:85], v[232:235], v[220:223], v[82:85]
	v_mfma_f32_16x16x32_bf16 v[78:81], v[216:219], v[236:239], v[78:81]
	s_add_u32 m0, s6, 0x2000
	v_lshl_add_u64 v[204:205], v[192:193], 0, s[0:1]
	global_load_lds_dwordx4 v[204:205], off
	v_mfma_f32_16x16x32_bf16 v[62:65], v[224:227], v[236:239], v[62:65]
	v_mfma_f32_16x16x32_bf16 v[46:49], v[228:231], v[236:239], v[46:49]
	s_add_u32 m0, s6, 0x3000
	v_lshl_add_u64 v[206:207], v[194:195], 0, s[0:1]
	global_load_lds_dwordx4 v[206:207], off
	v_mfma_f32_16x16x32_bf16 v[26:29], v[232:235], v[236:239], v[26:29]
	v_mfma_f32_16x16x32_bf16 v[38:41], v[216:219], v[240:243], v[38:41]
	s_add_u32 m0, s6, 0x4000
	v_lshl_add_u64 v[204:205], v[196:197], 0, s[0:1]
	global_load_lds_dwordx4 v[204:205], off
	v_mfma_f32_16x16x32_bf16 v[30:33], v[224:227], v[240:243], v[30:33]
	v_mfma_f32_16x16x32_bf16 v[22:25], v[228:231], v[240:243], v[22:25]
	s_add_u32 m0, s6, 0x5000
	v_lshl_add_u64 v[206:207], v[198:199], 0, s[0:1]
	global_load_lds_dwordx4 v[206:207], off
	v_mfma_f32_16x16x32_bf16 v[18:21], v[232:235], v[240:243], v[18:21]
	v_mfma_f32_16x16x32_bf16 v[14:17], v[216:219], v[244:247], v[14:17]
	s_add_u32 m0, s6, 0x6000
	v_lshl_add_u64 v[204:205], v[200:201], 0, s[0:1]
	global_load_lds_dwordx4 v[204:205], off
	v_mfma_f32_16x16x32_bf16 v[10:13], v[224:227], v[244:247], v[10:13]
	v_mfma_f32_16x16x32_bf16 v[6:9], v[228:231], v[244:247], v[6:9]
	s_add_u32 m0, s6, 0x7000
	v_lshl_add_u64 v[206:207], v[202:203], 0, s[0:1]
	global_load_lds_dwordx4 v[206:207], off
	v_mfma_f32_16x16x32_bf16 v[2:5], v[232:235], v[244:247], v[2:5]
	s_setprio 0
	s_waitcnt vmcnt(8)
	s_barrier
	ds_read_b128 v[152:155], v112 offset:49152
	ds_read_b128 v[156:159], v110 offset:32768
	ds_read_b128 v[160:163], v112 offset:51200
	ds_read_b128 v[164:167], v112 offset:53248
	ds_read_b128 v[168:171], v113 offset:49152
	ds_read_b128 v[172:175], v110 offset:34816
	ds_read_b128 v[208:211], v110 offset:36864
	ds_read_b128 v[212:215], v111 offset:32768
	ds_read_b128 v[216:219], v116 offset:49152
	ds_read_b128 v[220:223], v114 offset:32768
	ds_read_b128 v[224:227], v116 offset:51200
	ds_read_b128 v[228:231], v116 offset:53248
	ds_read_b128 v[232:235], v117 offset:49152
	ds_read_b128 v[236:239], v114 offset:34816
	ds_read_b128 v[240:243], v114 offset:36864
	ds_read_b128 v[244:247], v115 offset:32768
	s_setprio 1
	s_waitcnt lgkmcnt(14)
	v_mfma_f32_16x16x32_bf16 v[94:97], v[152:155], v[156:159], v[94:97]
	s_waitcnt lgkmcnt(13)
	v_mfma_f32_16x16x32_bf16 v[90:93], v[160:163], v[156:159], v[90:93]
	s_waitcnt lgkmcnt(12)
	v_mfma_f32_16x16x32_bf16 v[86:89], v[164:167], v[156:159], v[86:89]
	s_waitcnt lgkmcnt(11)
	v_mfma_f32_16x16x32_bf16 v[82:85], v[168:171], v[156:159], v[82:85]
	s_waitcnt lgkmcnt(10)
	v_mfma_f32_16x16x32_bf16 v[78:81], v[152:155], v[172:175], v[78:81]
	v_mfma_f32_16x16x32_bf16 v[62:65], v[160:163], v[172:175], v[62:65]
	v_mfma_f32_16x16x32_bf16 v[46:49], v[164:167], v[172:175], v[46:49]
	v_mfma_f32_16x16x32_bf16 v[26:29], v[168:171], v[172:175], v[26:29]
	s_waitcnt lgkmcnt(9)
	v_mfma_f32_16x16x32_bf16 v[38:41], v[152:155], v[208:211], v[38:41]
	v_mfma_f32_16x16x32_bf16 v[30:33], v[160:163], v[208:211], v[30:33]
	v_mfma_f32_16x16x32_bf16 v[22:25], v[164:167], v[208:211], v[22:25]
	v_mfma_f32_16x16x32_bf16 v[18:21], v[168:171], v[208:211], v[18:21]
	s_waitcnt lgkmcnt(8)
	v_mfma_f32_16x16x32_bf16 v[14:17], v[152:155], v[212:215], v[14:17]
	v_mfma_f32_16x16x32_bf16 v[10:13], v[160:163], v[212:215], v[10:13]
	v_mfma_f32_16x16x32_bf16 v[6:9], v[164:167], v[212:215], v[6:9]
	v_mfma_f32_16x16x32_bf16 v[2:5], v[168:171], v[212:215], v[2:5]
	s_setprio 0
	s_waitcnt lgkmcnt(0)
	s_barrier
	s_add_i32 s0, s5, 0xc0
	s_min_u32 s0, s0, 0x3c0
	s_lshl_b32 s0, s0, 1
	s_setprio 1
	v_mfma_f32_16x16x32_bf16 v[94:97], v[216:219], v[220:223], v[94:97]
	s_add_u32 m0, s6, 0x8000
	v_lshl_add_u64 v[204:205], v[188:189], 0, s[0:1]
	global_load_lds_dwordx4 v[204:205], off
	v_mfma_f32_16x16x32_bf16 v[90:93], v[224:227], v[220:223], v[90:93]
	v_mfma_f32_16x16x32_bf16 v[86:89], v[228:231], v[220:223], v[86:89]
	s_add_u32 m0, s6, 0x9000
	v_lshl_add_u64 v[206:207], v[190:191], 0, s[0:1]
	global_load_lds_dwordx4 v[206:207], off
	v_mfma_f32_16x16x32_bf16 v[82:85], v[232:235], v[220:223], v[82:85]
	v_mfma_f32_16x16x32_bf16 v[78:81], v[216:219], v[236:239], v[78:81]
	s_add_u32 m0, s6, 0xa000
	v_lshl_add_u64 v[204:205], v[192:193], 0, s[0:1]
	global_load_lds_dwordx4 v[204:205], off
	v_mfma_f32_16x16x32_bf16 v[62:65], v[224:227], v[236:239], v[62:65]
	v_mfma_f32_16x16x32_bf16 v[46:49], v[228:231], v[236:239], v[46:49]
	s_add_u32 m0, s6, 0xb000
	v_lshl_add_u64 v[206:207], v[194:195], 0, s[0:1]
	global_load_lds_dwordx4 v[206:207], off
	v_mfma_f32_16x16x32_bf16 v[26:29], v[232:235], v[236:239], v[26:29]
	v_mfma_f32_16x16x32_bf16 v[38:41], v[216:219], v[240:243], v[38:41]
	s_add_u32 m0, s6, 0xc000
	v_lshl_add_u64 v[204:205], v[196:197], 0, s[0:1]
	global_load_lds_dwordx4 v[204:205], off
	v_mfma_f32_16x16x32_bf16 v[30:33], v[224:227], v[240:243], v[30:33]
	v_mfma_f32_16x16x32_bf16 v[22:25], v[228:231], v[240:243], v[22:25]
	s_add_u32 m0, s6, 0xd000
	v_lshl_add_u64 v[206:207], v[198:199], 0, s[0:1]
	global_load_lds_dwordx4 v[206:207], off
	v_mfma_f32_16x16x32_bf16 v[18:21], v[232:235], v[240:243], v[18:21]
	v_mfma_f32_16x16x32_bf16 v[14:17], v[216:219], v[244:247], v[14:17]
	s_add_u32 m0, s6, 0xe000
	v_lshl_add_u64 v[204:205], v[200:201], 0, s[0:1]
	global_load_lds_dwordx4 v[204:205], off
	v_mfma_f32_16x16x32_bf16 v[10:13], v[224:227], v[244:247], v[10:13]
	v_mfma_f32_16x16x32_bf16 v[6:9], v[228:231], v[244:247], v[6:9]
	s_add_u32 m0, s6, 0xf000
	v_lshl_add_u64 v[206:207], v[202:203], 0, s[0:1]
	global_load_lds_dwordx4 v[206:207], off
	v_mfma_f32_16x16x32_bf16 v[2:5], v[232:235], v[244:247], v[2:5]
	s_setprio 0
	s_waitcnt vmcnt(8)
	s_barrier
	s_add_i32 s5, s5, 0x80
	s_add_i32 s4, s4, 2
	s_cmp_gt_u32 s4, 13
	s_cbranch_scc0 .Lglds2_2829
	s_waitcnt vmcnt(0)
	v_readlane_b32 s36, v254, 40
	s_waitcnt vmcnt(7)
	v_or_b32_e32 v35, s2, v118
	v_readlane_b32 s48, v254, 52
	v_readlane_b32 s49, v254, 53
	v_or_b32_e32 v34, s3, v119
	s_waitcnt vmcnt(6)
	v_add_u32_e32 v42, v35, v120
	v_mov_b64_e32 v[36:37], s[48:49]
	v_mad_i64_i32 v[36:37], s[2:3], v42, s18, v[36:37]
	v_cmp_gt_i32_e32 vcc, s19, v34
	v_ashrrev_i32_e32 v35, 31, v34
	v_readlane_b32 s37, v254, 41
	v_readlane_b32 s38, v254, 42
	v_readlane_b32 s39, v254, 43
	v_readlane_b32 s40, v254, 44
	v_readlane_b32 s41, v254, 45
	v_readlane_b32 s42, v254, 46
	v_readlane_b32 s43, v254, 47
	v_readlane_b32 s44, v254, 48
	v_readlane_b32 s45, v254, 49
	v_readlane_b32 s46, v254, 50
	v_readlane_b32 s47, v254, 51
	v_readlane_b32 s50, v254, 54
	v_readlane_b32 s51, v254, 55
	s_and_saveexec_b64 s[2:3], vcc
	s_cbranch_execnz .LBB0_205
	s_or_b64 exec, exec, s[2:3]
	v_cmp_gt_i32_e64 s[4:5], s20, v34
	s_and_saveexec_b64 s[2:3], s[4:5]
	s_cbranch_execnz .LBB0_206

.Lglds2_3547:
	ds_read_b128 v[152:155], v112 offset:16384
	ds_read_b128 v[156:159], v110
	ds_read_b128 v[160:163], v112 offset:18432
	ds_read_b128 v[164:167], v112 offset:20480
	ds_read_b128 v[168:171], v113 offset:16384
	ds_read_b128 v[172:175], v110 offset:2048
	ds_read_b128 v[208:211], v110 offset:4096
	ds_read_b128 v[212:215], v111
	ds_read_b128 v[216:219], v116 offset:16384
	ds_read_b128 v[220:223], v114
	ds_read_b128 v[224:227], v116 offset:18432
	ds_read_b128 v[228:231], v116 offset:20480
	ds_read_b128 v[232:235], v117 offset:16384
	ds_read_b128 v[236:239], v114 offset:2048
	ds_read_b128 v[240:243], v114 offset:4096
	ds_read_b128 v[244:247], v115
	s_setprio 1
	s_waitcnt lgkmcnt(14)
	v_mfma_f32_16x16x32_bf16 v[94:97], v[152:155], v[156:159], v[94:97]
	s_waitcnt lgkmcnt(13)
	v_mfma_f32_16x16x32_bf16 v[90:93], v[160:163], v[156:159], v[90:93]
	s_waitcnt lgkmcnt(12)
	v_mfma_f32_16x16x32_bf16 v[86:89], v[164:167], v[156:159], v[86:89]
	s_waitcnt lgkmcnt(11)
	v_mfma_f32_16x16x32_bf16 v[82:85], v[168:171], v[156:159], v[82:85]
	s_waitcnt lgkmcnt(10)
	v_mfma_f32_16x16x32_bf16 v[78:81], v[152:155], v[172:175], v[78:81]
	v_mfma_f32_16x16x32_bf16 v[54:57], v[160:163], v[172:175], v[54:57]
	v_mfma_f32_16x16x32_bf16 v[38:41], v[164:167], v[172:175], v[38:41]
	v_mfma_f32_16x16x32_bf16 v[34:37], v[168:171], v[172:175], v[34:37]
	s_waitcnt lgkmcnt(9)
	v_mfma_f32_16x16x32_bf16 v[74:77], v[152:155], v[208:211], v[74:77]
	v_mfma_f32_16x16x32_bf16 v[70:73], v[160:163], v[208:211], v[70:73]
	v_mfma_f32_16x16x32_bf16 v[66:69], v[164:167], v[208:211], v[66:69]
	v_mfma_f32_16x16x32_bf16 v[62:65], v[168:171], v[208:211], v[62:65]
	s_waitcnt lgkmcnt(8)
	v_mfma_f32_16x16x32_bf16 v[58:61], v[152:155], v[212:215], v[58:61]
	v_mfma_f32_16x16x32_bf16 v[50:53], v[160:163], v[212:215], v[50:53]
	v_mfma_f32_16x16x32_bf16 v[46:49], v[164:167], v[212:215], v[46:49]
	v_mfma_f32_16x16x32_bf16 v[42:45], v[168:171], v[212:215], v[42:45]
	s_setprio 0
	s_waitcnt lgkmcnt(0)
	s_barrier
	s_add_i32 s0, s19, 0x80
	s_min_u32 s0, s0, 0x3c0
	s_lshl_b32 s0, s0, 1
	s_setprio 1
	v_mfma_f32_16x16x32_bf16 v[94:97], v[216:219], v[220:223], v[94:97]
	s_add_u32 m0, s20, 0x0
	v_lshl_add_u64 v[204:205], v[188:189], 0, s[0:1]
	global_load_lds_dwordx4 v[204:205], off
	v_mfma_f32_16x16x32_bf16 v[90:93], v[224:227], v[220:223], v[90:93]
	v_mfma_f32_16x16x32_bf16 v[86:89], v[228:231], v[220:223], v[86:89]
	s_add_u32 m0, s20, 0x1000
	v_lshl_add_u64 v[206:207], v[190:191], 0, s[0:1]
	global_load_lds_dwordx4 v[206:207], off
	v_mfma_f32_16x16x32_bf16 v[82:85], v[232:235], v[220:223], v[82:85]
	v_mfma_f32_16x16x32_bf16 v[78:81], v[216:219], v[236:239], v[78:81]
	s_add_u32 m0, s20, 0x2000
	v_lshl_add_u64 v[204:205], v[192:193], 0, s[0:1]
	global_load_lds_dwordx4 v[204:205], off
	v_mfma_f32_16x16x32_bf16 v[54:57], v[224:227], v[236:239], v[54:57]
	v_mfma_f32_16x16x32_bf16 v[38:41], v[228:231], v[236:239], v[38:41]
	s_add_u32 m0, s20, 0x3000
	v_lshl_add_u64 v[206:207], v[194:195], 0, s[0:1]
	global_load_lds_dwordx4 v[206:207], off
	v_mfma_f32_16x16x32_bf16 v[34:37], v[232:235], v[236:239], v[34:37]
	v_mfma_f32_16x16x32_bf16 v[74:77], v[216:219], v[240:243], v[74:77]
	s_add_u32 m0, s20, 0x4000
	v_lshl_add_u64 v[204:205], v[196:197], 0, s[0:1]
	global_load_lds_dwordx4 v[204:205], off
	v_mfma_f32_16x16x32_bf16 v[70:73], v[224:227], v[240:243], v[70:73]
	v_mfma_f32_16x16x32_bf16 v[66:69], v[228:231], v[240:243], v[66:69]
	s_add_u32 m0, s20, 0x5000
	v_lshl_add_u64 v[206:207], v[198:199], 0, s[0:1]
	global_load_lds_dwordx4 v[206:207], off
	v_mfma_f32_16x16x32_bf16 v[62:65], v[232:235], v[240:243], v[62:65]
	v_mfma_f32_16x16x32_bf16 v[58:61], v[216:219], v[244:247], v[58:61]
	s_add_u32 m0, s20, 0x6000
	v_lshl_add_u64 v[204:205], v[200:201], 0, s[0:1]
	global_load_lds_dwordx4 v[204:205], off
	v_mfma_f32_16x16x32_bf16 v[50:53], v[224:227], v[244:247], v[50:53]
	v_mfma_f32_16x16x32_bf16 v[46:49], v[228:231], v[244:247], v[46:49]
	s_add_u32 m0, s20, 0x7000
	v_lshl_add_u64 v[206:207], v[202:203], 0, s[0:1]
	global_load_lds_dwordx4 v[206:207], off
	v_mfma_f32_16x16x32_bf16 v[42:45], v[232:235], v[244:247], v[42:45]
	s_setprio 0
	s_waitcnt vmcnt(8)
	s_barrier
	ds_read_b128 v[152:155], v112 offset:49152
	ds_read_b128 v[156:159], v110 offset:32768
	ds_read_b128 v[160:163], v112 offset:51200
	ds_read_b128 v[164:167], v112 offset:53248
	ds_read_b128 v[168:171], v113 offset:49152
	ds_read_b128 v[172:175], v110 offset:34816
	ds_read_b128 v[208:211], v110 offset:36864
	ds_read_b128 v[212:215], v111 offset:32768
	ds_read_b128 v[216:219], v116 offset:49152
	ds_read_b128 v[220:223], v114 offset:32768
	ds_read_b128 v[224:227], v116 offset:51200
	ds_read_b128 v[228:231], v116 offset:53248
	ds_read_b128 v[232:235], v117 offset:49152
	ds_read_b128 v[236:239], v114 offset:34816
	ds_read_b128 v[240:243], v114 offset:36864
	ds_read_b128 v[244:247], v115 offset:32768
	s_setprio 1
	s_waitcnt lgkmcnt(14)
	v_mfma_f32_16x16x32_bf16 v[94:97], v[152:155], v[156:159], v[94:97]
	s_waitcnt lgkmcnt(13)
	v_mfma_f32_16x16x32_bf16 v[90:93], v[160:163], v[156:159], v[90:93]
	s_waitcnt lgkmcnt(12)
	v_mfma_f32_16x16x32_bf16 v[86:89], v[164:167], v[156:159], v[86:89]
	s_waitcnt lgkmcnt(11)
	v_mfma_f32_16x16x32_bf16 v[82:85], v[168:171], v[156:159], v[82:85]
	s_waitcnt lgkmcnt(10)
	v_mfma_f32_16x16x32_bf16 v[78:81], v[152:155], v[172:175], v[78:81]
	v_mfma_f32_16x16x32_bf16 v[54:57], v[160:163], v[172:175], v[54:57]
	v_mfma_f32_16x16x32_bf16 v[38:41], v[164:167], v[172:175], v[38:41]
	v_mfma_f32_16x16x32_bf16 v[34:37], v[168:171], v[172:175], v[34:37]
	s_waitcnt lgkmcnt(9)
	v_mfma_f32_16x16x32_bf16 v[74:77], v[152:155], v[208:211], v[74:77]
	v_mfma_f32_16x16x32_bf16 v[70:73], v[160:163], v[208:211], v[70:73]
	v_mfma_f32_16x16x32_bf16 v[66:69], v[164:167], v[208:211], v[66:69]
	v_mfma_f32_16x16x32_bf16 v[62:65], v[168:171], v[208:211], v[62:65]
	s_waitcnt lgkmcnt(8)
	v_mfma_f32_16x16x32_bf16 v[58:61], v[152:155], v[212:215], v[58:61]
	v_mfma_f32_16x16x32_bf16 v[50:53], v[160:163], v[212:215], v[50:53]
	v_mfma_f32_16x16x32_bf16 v[46:49], v[164:167], v[212:215], v[46:49]
	v_mfma_f32_16x16x32_bf16 v[42:45], v[168:171], v[212:215], v[42:45]
	s_setprio 0
	s_waitcnt lgkmcnt(0)
	s_barrier
	s_add_i32 s0, s19, 0xc0
	s_min_u32 s0, s0, 0x3c0
	s_lshl_b32 s0, s0, 1
	s_setprio 1
	v_mfma_f32_16x16x32_bf16 v[94:97], v[216:219], v[220:223], v[94:97]
	s_add_u32 m0, s20, 0x8000
	v_lshl_add_u64 v[204:205], v[188:189], 0, s[0:1]
	global_load_lds_dwordx4 v[204:205], off
	v_mfma_f32_16x16x32_bf16 v[90:93], v[224:227], v[220:223], v[90:93]
	v_mfma_f32_16x16x32_bf16 v[86:89], v[228:231], v[220:223], v[86:89]
	s_add_u32 m0, s20, 0x9000
	v_lshl_add_u64 v[206:207], v[190:191], 0, s[0:1]
	global_load_lds_dwordx4 v[206:207], off
	v_mfma_f32_16x16x32_bf16 v[82:85], v[232:235], v[220:223], v[82:85]
	v_mfma_f32_16x16x32_bf16 v[78:81], v[216:219], v[236:239], v[78:81]
	s_add_u32 m0, s20, 0xa000
	v_lshl_add_u64 v[204:205], v[192:193], 0, s[0:1]
	global_load_lds_dwordx4 v[204:205], off
	v_mfma_f32_16x16x32_bf16 v[54:57], v[224:227], v[236:239], v[54:57]
	v_mfma_f32_16x16x32_bf16 v[38:41], v[228:231], v[236:239], v[38:41]
	s_add_u32 m0, s20, 0xb000
	v_lshl_add_u64 v[206:207], v[194:195], 0, s[0:1]
	global_load_lds_dwordx4 v[206:207], off
	v_mfma_f32_16x16x32_bf16 v[34:37], v[232:235], v[236:239], v[34:37]
	v_mfma_f32_16x16x32_bf16 v[74:77], v[216:219], v[240:243], v[74:77]
	s_add_u32 m0, s20, 0xc000
	v_lshl_add_u64 v[204:205], v[196:197], 0, s[0:1]
	global_load_lds_dwordx4 v[204:205], off
	v_mfma_f32_16x16x32_bf16 v[70:73], v[224:227], v[240:243], v[70:73]
	v_mfma_f32_16x16x32_bf16 v[66:69], v[228:231], v[240:243], v[66:69]
	s_add_u32 m0, s20, 0xd000
	v_lshl_add_u64 v[206:207], v[198:199], 0, s[0:1]
	global_load_lds_dwordx4 v[206:207], off
	v_mfma_f32_16x16x32_bf16 v[62:65], v[232:235], v[240:243], v[62:65]
	v_mfma_f32_16x16x32_bf16 v[58:61], v[216:219], v[244:247], v[58:61]
	s_add_u32 m0, s20, 0xe000
	v_lshl_add_u64 v[204:205], v[200:201], 0, s[0:1]
	global_load_lds_dwordx4 v[204:205], off
	v_mfma_f32_16x16x32_bf16 v[50:53], v[224:227], v[244:247], v[50:53]
	v_mfma_f32_16x16x32_bf16 v[46:49], v[228:231], v[244:247], v[46:49]
	s_add_u32 m0, s20, 0xf000
	v_lshl_add_u64 v[206:207], v[202:203], 0, s[0:1]
	global_load_lds_dwordx4 v[206:207], off
	v_mfma_f32_16x16x32_bf16 v[42:45], v[232:235], v[244:247], v[42:45]
	s_setprio 0
	s_waitcnt vmcnt(8)
	s_barrier
	s_add_i32 s19, s19, 0x80
	s_add_i32 s18, s18, 2
	s_cmp_lt_u32 s18, 14
	s_cbranch_scc1 .Lglds2_3547
	s_waitcnt vmcnt(0)
	v_readlane_b32 s36, v254, 40
	s_lshl_b64 s[12:13], s[12:13], 21
	v_readlane_b32 s50, v254, 54
	v_readlane_b32 s51, v254, 55
	s_add_u32 s12, s50, s12
	s_addc_u32 s13, s51, s13
	s_waitcnt vmcnt(7)
	v_or_b32_e32 v4, s17, v119
	v_add_lshl_u32 v98, v118, s16, 10
	v_lshl_add_u64 v[2:3], s[12:13], 0, v[98:99]
	v_lshlrev_b32_e32 v98, 1, v4
	v_lshl_add_u64 v[4:5], v[2:3], 0, v[98:99]
	s_waitcnt vmcnt(6)
	v_cvt_pk_bf16_f32 v6, v94, v95
	v_cvt_pk_bf16_f32 v7, v96, v97
	global_store_dwordx2 v[4:5], v[6:7], off
	v_cvt_pk_bf16_f32 v6, v90, v91
	v_cvt_pk_bf16_f32 v7, v92, v93
	global_store_dwordx2 v[4:5], v[6:7], off offset:32
	v_cvt_pk_bf16_f32 v6, v86, v87
	v_cvt_pk_bf16_f32 v7, v88, v89
	global_store_dwordx2 v[4:5], v[6:7], off offset:64
	v_cvt_pk_bf16_f32 v6, v82, v83
	v_cvt_pk_bf16_f32 v7, v84, v85
	global_store_dwordx2 v[4:5], v[6:7], off offset:96
	v_lshl_add_u64 v[4:5], v[2:3], 0, s[4:5]
	v_lshl_add_u64 v[6:7], v[4:5], 0, v[98:99]
	v_cvt_pk_bf16_f32 v8, v78, v79
	v_cvt_pk_bf16_f32 v9, v80, v81
	global_store_dwordx2 v[6:7], v[8:9], off
	v_or_b32_e32 v6, 32, v98
	v_mov_b32_e32 v7, v99
	v_lshl_add_u64 v[8:9], v[4:5], 0, v[6:7]
	s_waitcnt vmcnt(10)
	v_cvt_pk_bf16_f32 v10, v54, v55
	v_cvt_pk_bf16_f32 v11, v56, v57
	global_store_dwordx2 v[8:9], v[10:11], off
	v_or_b32_e32 v8, 64, v98
	v_mov_b32_e32 v9, v99
	v_lshl_add_u64 v[10:11], v[4:5], 0, v[8:9]
	v_cvt_pk_bf16_f32 v12, v38, v39
	v_cvt_pk_bf16_f32 v13, v40, v41
	global_store_dwordx2 v[10:11], v[12:13], off
	v_or_b32_e32 v10, 0x60, v98
	v_mov_b32_e32 v11, v99
	v_lshl_add_u64 v[4:5], v[4:5], 0, v[10:11]
	v_cvt_pk_bf16_f32 v12, v34, v35
	v_cvt_pk_bf16_f32 v13, v36, v37
	global_store_dwordx2 v[4:5], v[12:13], off
	v_lshl_add_u64 v[4:5], v[2:3], 0, s[6:7]
	v_lshl_add_u64 v[12:13], v[4:5], 0, v[98:99]
	s_waitcnt vmcnt(11)
	v_cvt_pk_bf16_f32 v14, v74, v75
	v_cvt_pk_bf16_f32 v15, v76, v77
	global_store_dwordx2 v[12:13], v[14:15], off
	v_lshl_add_u64 v[12:13], v[4:5], 0, v[6:7]
	v_cvt_pk_bf16_f32 v14, v70, v71
	v_cvt_pk_bf16_f32 v15, v72, v73
	global_store_dwordx2 v[12:13], v[14:15], off
	v_lshl_add_u64 v[12:13], v[4:5], 0, v[8:9]
	v_cvt_pk_bf16_f32 v14, v66, v67
	v_cvt_pk_bf16_f32 v15, v68, v69
	global_store_dwordx2 v[12:13], v[14:15], off
	v_lshl_add_u64 v[4:5], v[4:5], 0, v[10:11]
	v_cvt_pk_bf16_f32 v12, v62, v63
	v_cvt_pk_bf16_f32 v13, v64, v65
	v_lshl_add_u64 v[2:3], v[2:3], 0, s[8:9]
	global_store_dwordx2 v[4:5], v[12:13], off
	v_lshl_add_u64 v[4:5], v[2:3], 0, v[98:99]
	v_cvt_pk_bf16_f32 v12, v58, v59
	v_cvt_pk_bf16_f32 v13, v60, v61
	global_store_dwordx2 v[4:5], v[12:13], off
	v_lshl_add_u64 v[4:5], v[2:3], 0, v[6:7]
	v_cvt_pk_bf16_f32 v6, v50, v51
	v_cvt_pk_bf16_f32 v7, v52, v53
	v_readlane_b32 s12, v254, 0
	global_store_dwordx2 v[4:5], v[6:7], off
	v_lshl_add_u64 v[4:5], v[2:3], 0, v[8:9]
	v_cvt_pk_bf16_f32 v6, v46, v47
	v_cvt_pk_bf16_f32 v7, v48, v49
	s_add_i32 s2, s2, s12
	v_readlane_b32 s37, v254, 41
	global_store_dwordx2 v[4:5], v[6:7], off
	v_lshl_add_u64 v[2:3], v[2:3], 0, v[10:11]
	v_cvt_pk_bf16_f32 v4, v42, v43
	v_cvt_pk_bf16_f32 v5, v44, v45
	s_cmpk_lt_i32 s2, 0x80
	v_readlane_b32 s38, v254, 42
	v_readlane_b32 s39, v254, 43
	v_readlane_b32 s40, v254, 44
	v_readlane_b32 s41, v254, 45
	v_readlane_b32 s42, v254, 46
	v_readlane_b32 s43, v254, 47
	v_readlane_b32 s44, v254, 48
	v_readlane_b32 s45, v254, 49
	v_readlane_b32 s46, v254, 50
	v_readlane_b32 s47, v254, 51
	v_readlane_b32 s48, v254, 52
	v_readlane_b32 s49, v254, 53
	v_readlane_b32 s13, v254, 1
	global_store_dwordx2 v[2:3], v[4:5], off
	s_cbranch_scc1 .LBB0_220

.Lglds2_12468:
	ds_read_b128 v[152:155], v112 offset:16384
	ds_read_b128 v[156:159], v110
	ds_read_b128 v[160:163], v112 offset:18432
	ds_read_b128 v[164:167], v112 offset:20480
	ds_read_b128 v[168:171], v113 offset:16384
	ds_read_b128 v[172:175], v110 offset:2048
	ds_read_b128 v[204:207], v110 offset:4096
	ds_read_b128 v[208:211], v111
	ds_read_b128 v[212:215], v116 offset:16384
	ds_read_b128 v[216:219], v114
	ds_read_b128 v[220:223], v116 offset:18432
	ds_read_b128 v[224:227], v116 offset:20480
	ds_read_b128 v[228:231], v117 offset:16384
	ds_read_b128 v[232:235], v114 offset:2048
	ds_read_b128 v[236:239], v114 offset:4096
	ds_read_b128 v[240:243], v115
	s_setprio 1
	s_waitcnt lgkmcnt(14)
	v_mfma_f32_16x16x32_bf16 v[94:97], v[152:155], v[156:159], v[94:97]
	s_waitcnt lgkmcnt(13)
	v_mfma_f32_16x16x32_bf16 v[90:93], v[160:163], v[156:159], v[90:93]
	s_waitcnt lgkmcnt(12)
	v_mfma_f32_16x16x32_bf16 v[86:89], v[164:167], v[156:159], v[86:89]
	s_waitcnt lgkmcnt(11)
	v_mfma_f32_16x16x32_bf16 v[82:85], v[168:171], v[156:159], v[82:85]
	s_waitcnt lgkmcnt(10)
	v_mfma_f32_16x16x32_bf16 v[78:81], v[152:155], v[172:175], v[78:81]
	v_mfma_f32_16x16x32_bf16 v[74:77], v[160:163], v[172:175], v[74:77]
	v_mfma_f32_16x16x32_bf16 v[62:65], v[164:167], v[172:175], v[62:65]
	v_mfma_f32_16x16x32_bf16 v[30:33], v[168:171], v[172:175], v[30:33]
	s_waitcnt lgkmcnt(9)
	v_mfma_f32_16x16x32_bf16 v[66:69], v[152:155], v[204:207], v[66:69]
	v_mfma_f32_16x16x32_bf16 v[38:41], v[160:163], v[204:207], v[38:41]
	v_mfma_f32_16x16x32_bf16 v[34:37], v[164:167], v[204:207], v[34:37]
	v_mfma_f32_16x16x32_bf16 v[18:21], v[168:171], v[204:207], v[18:21]
	s_waitcnt lgkmcnt(8)
	v_mfma_f32_16x16x32_bf16 v[14:17], v[152:155], v[208:211], v[14:17]
	v_mfma_f32_16x16x32_bf16 v[10:13], v[160:163], v[208:211], v[10:13]
	v_mfma_f32_16x16x32_bf16 v[6:9], v[164:167], v[208:211], v[6:9]
	v_mfma_f32_16x16x32_bf16 v[2:5], v[168:171], v[208:211], v[2:5]
	s_setprio 0
	s_waitcnt lgkmcnt(0)
	s_barrier
	s_add_i32 s4, s14, 0x80
	s_min_u32 s4, s4, 0x3c0
	s_lshl_b32 s4, s4, 1
	s_setprio 1
	v_mfma_f32_16x16x32_bf16 v[94:97], v[212:215], v[216:219], v[94:97]
	s_add_u32 m0, s15, 0x0
	v_lshl_add_u64 v[200:201], v[184:185], 0, s[4:5]
	global_load_lds_dwordx4 v[200:201], off
	v_mfma_f32_16x16x32_bf16 v[90:93], v[220:223], v[216:219], v[90:93]
	v_mfma_f32_16x16x32_bf16 v[86:89], v[224:227], v[216:219], v[86:89]
	s_add_u32 m0, s15, 0x1000
	v_lshl_add_u64 v[202:203], v[186:187], 0, s[4:5]
	global_load_lds_dwordx4 v[202:203], off
	v_mfma_f32_16x16x32_bf16 v[82:85], v[228:231], v[216:219], v[82:85]
	v_mfma_f32_16x16x32_bf16 v[78:81], v[212:215], v[232:235], v[78:81]
	s_add_u32 m0, s15, 0x2000
	v_lshl_add_u64 v[200:201], v[188:189], 0, s[4:5]
	global_load_lds_dwordx4 v[200:201], off
	v_mfma_f32_16x16x32_bf16 v[74:77], v[220:223], v[232:235], v[74:77]
	v_mfma_f32_16x16x32_bf16 v[62:65], v[224:227], v[232:235], v[62:65]
	s_add_u32 m0, s15, 0x3000
	v_lshl_add_u64 v[202:203], v[190:191], 0, s[4:5]
	global_load_lds_dwordx4 v[202:203], off
	v_mfma_f32_16x16x32_bf16 v[30:33], v[228:231], v[232:235], v[30:33]
	v_mfma_f32_16x16x32_bf16 v[66:69], v[212:215], v[236:239], v[66:69]
	s_add_u32 m0, s15, 0x4000
	v_lshl_add_u64 v[200:201], v[192:193], 0, s[4:5]
	global_load_lds_dwordx4 v[200:201], off
	v_mfma_f32_16x16x32_bf16 v[38:41], v[220:223], v[236:239], v[38:41]
	v_mfma_f32_16x16x32_bf16 v[34:37], v[224:227], v[236:239], v[34:37]
	s_add_u32 m0, s15, 0x5000
	v_lshl_add_u64 v[202:203], v[194:195], 0, s[4:5]
	global_load_lds_dwordx4 v[202:203], off
	v_mfma_f32_16x16x32_bf16 v[18:21], v[228:231], v[236:239], v[18:21]
	v_mfma_f32_16x16x32_bf16 v[14:17], v[212:215], v[240:243], v[14:17]
	s_add_u32 m0, s15, 0x6000
	v_lshl_add_u64 v[200:201], v[196:197], 0, s[4:5]
	global_load_lds_dwordx4 v[200:201], off
	v_mfma_f32_16x16x32_bf16 v[10:13], v[220:223], v[240:243], v[10:13]
	v_mfma_f32_16x16x32_bf16 v[6:9], v[224:227], v[240:243], v[6:9]
	s_add_u32 m0, s15, 0x7000
	v_lshl_add_u64 v[202:203], v[198:199], 0, s[4:5]
	global_load_lds_dwordx4 v[202:203], off
	v_mfma_f32_16x16x32_bf16 v[2:5], v[228:231], v[240:243], v[2:5]
	s_setprio 0
	s_waitcnt vmcnt(8)
	s_barrier
	ds_read_b128 v[152:155], v112 offset:49152
	ds_read_b128 v[156:159], v110 offset:32768
	ds_read_b128 v[160:163], v112 offset:51200
	ds_read_b128 v[164:167], v112 offset:53248
	ds_read_b128 v[168:171], v113 offset:49152
	ds_read_b128 v[172:175], v110 offset:34816
	ds_read_b128 v[204:207], v110 offset:36864
	ds_read_b128 v[208:211], v111 offset:32768
	ds_read_b128 v[212:215], v116 offset:49152
	ds_read_b128 v[216:219], v114 offset:32768
	ds_read_b128 v[220:223], v116 offset:51200
	ds_read_b128 v[224:227], v116 offset:53248
	ds_read_b128 v[228:231], v117 offset:49152
	ds_read_b128 v[232:235], v114 offset:34816
	ds_read_b128 v[236:239], v114 offset:36864
	ds_read_b128 v[240:243], v115 offset:32768
	s_setprio 1
	s_waitcnt lgkmcnt(14)
	v_mfma_f32_16x16x32_bf16 v[94:97], v[152:155], v[156:159], v[94:97]
	s_waitcnt lgkmcnt(13)
	v_mfma_f32_16x16x32_bf16 v[90:93], v[160:163], v[156:159], v[90:93]
	s_waitcnt lgkmcnt(12)
	v_mfma_f32_16x16x32_bf16 v[86:89], v[164:167], v[156:159], v[86:89]
	s_waitcnt lgkmcnt(11)
	v_mfma_f32_16x16x32_bf16 v[82:85], v[168:171], v[156:159], v[82:85]
	s_waitcnt lgkmcnt(10)
	v_mfma_f32_16x16x32_bf16 v[78:81], v[152:155], v[172:175], v[78:81]
	v_mfma_f32_16x16x32_bf16 v[74:77], v[160:163], v[172:175], v[74:77]
	v_mfma_f32_16x16x32_bf16 v[62:65], v[164:167], v[172:175], v[62:65]
	v_mfma_f32_16x16x32_bf16 v[30:33], v[168:171], v[172:175], v[30:33]
	s_waitcnt lgkmcnt(9)
	v_mfma_f32_16x16x32_bf16 v[66:69], v[152:155], v[204:207], v[66:69]
	v_mfma_f32_16x16x32_bf16 v[38:41], v[160:163], v[204:207], v[38:41]
	v_mfma_f32_16x16x32_bf16 v[34:37], v[164:167], v[204:207], v[34:37]
	v_mfma_f32_16x16x32_bf16 v[18:21], v[168:171], v[204:207], v[18:21]
	s_waitcnt lgkmcnt(8)
	v_mfma_f32_16x16x32_bf16 v[14:17], v[152:155], v[208:211], v[14:17]
	v_mfma_f32_16x16x32_bf16 v[10:13], v[160:163], v[208:211], v[10:13]
	v_mfma_f32_16x16x32_bf16 v[6:9], v[164:167], v[208:211], v[6:9]
	v_mfma_f32_16x16x32_bf16 v[2:5], v[168:171], v[208:211], v[2:5]
	s_setprio 0
	s_waitcnt lgkmcnt(0)
	s_barrier
	s_add_i32 s4, s14, 0xc0
	s_min_u32 s4, s4, 0x3c0
	s_lshl_b32 s4, s4, 1
	s_setprio 1
	v_mfma_f32_16x16x32_bf16 v[94:97], v[212:215], v[216:219], v[94:97]
	s_add_u32 m0, s15, 0x8000
	v_lshl_add_u64 v[200:201], v[184:185], 0, s[4:5]
	global_load_lds_dwordx4 v[200:201], off
	v_mfma_f32_16x16x32_bf16 v[90:93], v[220:223], v[216:219], v[90:93]
	v_mfma_f32_16x16x32_bf16 v[86:89], v[224:227], v[216:219], v[86:89]
	s_add_u32 m0, s15, 0x9000
	v_lshl_add_u64 v[202:203], v[186:187], 0, s[4:5]
	global_load_lds_dwordx4 v[202:203], off
	v_mfma_f32_16x16x32_bf16 v[82:85], v[228:231], v[216:219], v[82:85]
	v_mfma_f32_16x16x32_bf16 v[78:81], v[212:215], v[232:235], v[78:81]
	s_add_u32 m0, s15, 0xa000
	v_lshl_add_u64 v[200:201], v[188:189], 0, s[4:5]
	global_load_lds_dwordx4 v[200:201], off
	v_mfma_f32_16x16x32_bf16 v[74:77], v[220:223], v[232:235], v[74:77]
	v_mfma_f32_16x16x32_bf16 v[62:65], v[224:227], v[232:235], v[62:65]
	s_add_u32 m0, s15, 0xb000
	v_lshl_add_u64 v[202:203], v[190:191], 0, s[4:5]
	global_load_lds_dwordx4 v[202:203], off
	v_mfma_f32_16x16x32_bf16 v[30:33], v[228:231], v[232:235], v[30:33]
	v_mfma_f32_16x16x32_bf16 v[66:69], v[212:215], v[236:239], v[66:69]
	s_add_u32 m0, s15, 0xc000
	v_lshl_add_u64 v[200:201], v[192:193], 0, s[4:5]
	global_load_lds_dwordx4 v[200:201], off
	v_mfma_f32_16x16x32_bf16 v[38:41], v[220:223], v[236:239], v[38:41]
	v_mfma_f32_16x16x32_bf16 v[34:37], v[224:227], v[236:239], v[34:37]
	s_add_u32 m0, s15, 0xd000
	v_lshl_add_u64 v[202:203], v[194:195], 0, s[4:5]
	global_load_lds_dwordx4 v[202:203], off
	v_mfma_f32_16x16x32_bf16 v[18:21], v[228:231], v[236:239], v[18:21]
	v_mfma_f32_16x16x32_bf16 v[14:17], v[212:215], v[240:243], v[14:17]
	s_add_u32 m0, s15, 0xe000
	v_lshl_add_u64 v[200:201], v[196:197], 0, s[4:5]
	global_load_lds_dwordx4 v[200:201], off
	v_mfma_f32_16x16x32_bf16 v[10:13], v[220:223], v[240:243], v[10:13]
	v_mfma_f32_16x16x32_bf16 v[6:9], v[224:227], v[240:243], v[6:9]
	s_add_u32 m0, s15, 0xf000
	v_lshl_add_u64 v[202:203], v[198:199], 0, s[4:5]
	global_load_lds_dwordx4 v[202:203], off
	v_mfma_f32_16x16x32_bf16 v[2:5], v[228:231], v[240:243], v[2:5]
	s_setprio 0
	s_waitcnt vmcnt(8)
	s_barrier
	s_add_i32 s14, s14, 0x80
	s_add_i32 s13, s13, 2
	s_cmp_lt_u32 s13, 14
	s_cbranch_scc1 .Lglds2_12468
	s_waitcnt vmcnt(0)
	s_waitcnt vmcnt(0)
	v_or_b32_e32 v170, s12, v119
	v_add_lshl_u32 v98, v118, s11, 10
	v_readlane_b32 s12, v254, 8
	v_readlane_b32 s13, v254, 9
	v_readlane_b32 s14, v254, 10
	v_readlane_b32 s15, v254, 11
	v_readlane_b32 s16, v254, 12
	v_readlane_b32 s17, v254, 13
	v_readlane_b32 s18, v254, 14
	v_readlane_b32 s19, v254, 15
	v_readlane_b32 s20, v254, 16
	v_readlane_b32 s21, v254, 17
	v_readlane_b32 s22, v254, 18
	v_readlane_b32 s23, v254, 19
	v_readlane_b32 s24, v254, 20
	v_readlane_b32 s25, v254, 21
	v_readlane_b32 s26, v254, 22
	v_readlane_b32 s27, v254, 23
	v_lshlrev_b32_e32 v168, 2, v170
	v_mov_b32_e32 v169, v99
	v_lshlrev_b64 v[174:175], 2, v[98:99]
	v_lshl_add_u64 v[152:153], s[12:13], 0, v[174:175]
	v_lshl_add_u64 v[160:161], s[82:83], 0, v[174:175]
	v_lshl_add_u64 v[152:153], v[152:153], 0, v[168:169]
	v_lshl_add_u64 v[160:161], v[160:161], 0, v[168:169]
	global_load_dwordx4 v[120:123], v[152:153], off
	global_load_dwordx4 v[124:127], v[152:153], off offset:64
	global_load_dwordx4 v[128:131], v[152:153], off offset:128
	global_load_dwordx4 v[132:135], v[152:153], off offset:192
	v_or_b32_e32 v172, 0x4000, v98
	v_mov_b32_e32 v173, v99
	v_lshlrev_b64 v[174:175], 2, v[172:173]
	v_lshl_add_u64 v[154:155], s[12:13], 0, v[174:175]
	v_lshl_add_u64 v[162:163], s[82:83], 0, v[174:175]
	v_lshl_add_u64 v[154:155], v[154:155], 0, v[168:169]
	v_lshl_add_u64 v[162:163], v[162:163], 0, v[168:169]
	global_load_dwordx4 v[136:139], v[154:155], off
	global_load_dwordx4 v[140:143], v[154:155], off offset:64
	global_load_dwordx4 v[144:147], v[154:155], off offset:128
	global_load_dwordx4 v[148:151], v[154:155], off offset:192
	v_or_b32_e32 v172, 0x8000, v98
	v_mov_b32_e32 v173, v99
	v_lshlrev_b64 v[174:175], 2, v[172:173]
	v_lshl_add_u64 v[156:157], s[12:13], 0, v[174:175]
	v_lshl_add_u64 v[164:165], s[82:83], 0, v[174:175]
	v_lshl_add_u64 v[156:157], v[156:157], 0, v[168:169]
	v_lshl_add_u64 v[164:165], v[164:165], 0, v[168:169]
	global_load_dwordx4 v[22:25], v[156:157], off
	global_load_dwordx4 v[26:29], v[156:157], off offset:64
	global_load_dwordx4 v[42:45], v[156:157], off offset:128
	global_load_dwordx4 v[46:49], v[156:157], off offset:192
	v_or_b32_e32 v172, 0xc000, v98
	v_mov_b32_e32 v173, v99
	v_lshlrev_b64 v[174:175], 2, v[172:173]
	v_lshl_add_u64 v[158:159], s[12:13], 0, v[174:175]
	v_lshl_add_u64 v[166:167], s[82:83], 0, v[174:175]
	v_lshl_add_u64 v[158:159], v[158:159], 0, v[168:169]
	v_lshl_add_u64 v[166:167], v[166:167], 0, v[168:169]
	global_load_dwordx4 v[50:53], v[158:159], off
	global_load_dwordx4 v[54:57], v[158:159], off offset:64
	global_load_dwordx4 v[58:61], v[158:159], off offset:128
	global_load_dwordx4 v[70:73], v[158:159], off offset:192
	s_waitcnt vmcnt(15)
	v_pk_fma_f32 v[120:121], v[120:121], s[6:7], v[94:95] op_sel_hi:[1,0,1]
	v_pk_fma_f32 v[122:123], v[122:123], s[6:7], v[96:97] op_sel_hi:[1,0,1]
	s_waitcnt vmcnt(14)
	v_pk_fma_f32 v[124:125], v[124:125], s[6:7], v[90:91] op_sel_hi:[1,0,1]
	v_pk_fma_f32 v[126:127], v[126:127], s[6:7], v[92:93] op_sel_hi:[1,0,1]
	s_waitcnt vmcnt(13)
	v_pk_fma_f32 v[128:129], v[128:129], s[6:7], v[86:87] op_sel_hi:[1,0,1]
	v_pk_fma_f32 v[130:131], v[130:131], s[6:7], v[88:89] op_sel_hi:[1,0,1]
	s_waitcnt vmcnt(12)
	v_pk_fma_f32 v[132:133], v[132:133], s[6:7], v[82:83] op_sel_hi:[1,0,1]
	v_pk_fma_f32 v[134:135], v[134:135], s[6:7], v[84:85] op_sel_hi:[1,0,1]
	s_waitcnt vmcnt(11)
	v_pk_fma_f32 v[136:137], v[136:137], s[6:7], v[78:79] op_sel_hi:[1,0,1]
	v_pk_fma_f32 v[138:139], v[138:139], s[6:7], v[80:81] op_sel_hi:[1,0,1]
	s_waitcnt vmcnt(10)
	v_pk_fma_f32 v[140:141], v[140:141], s[6:7], v[74:75] op_sel_hi:[1,0,1]
	v_pk_fma_f32 v[142:143], v[142:143], s[6:7], v[76:77] op_sel_hi:[1,0,1]
	s_waitcnt vmcnt(9)
	v_pk_fma_f32 v[144:145], v[144:145], s[6:7], v[62:63] op_sel_hi:[1,0,1]
	v_pk_fma_f32 v[146:147], v[146:147], s[6:7], v[64:65] op_sel_hi:[1,0,1]
	s_waitcnt vmcnt(8)
	v_pk_fma_f32 v[148:149], v[148:149], s[6:7], v[30:31] op_sel_hi:[1,0,1]
	v_pk_fma_f32 v[150:151], v[150:151], s[6:7], v[32:33] op_sel_hi:[1,0,1]
	s_waitcnt vmcnt(7)
	v_pk_fma_f32 v[22:23], v[22:23], s[6:7], v[66:67] op_sel_hi:[1,0,1]
	v_pk_fma_f32 v[24:25], v[24:25], s[6:7], v[68:69] op_sel_hi:[1,0,1]
	s_waitcnt vmcnt(6)
	v_pk_fma_f32 v[26:27], v[26:27], s[6:7], v[38:39] op_sel_hi:[1,0,1]
	v_pk_fma_f32 v[28:29], v[28:29], s[6:7], v[40:41] op_sel_hi:[1,0,1]
	s_waitcnt vmcnt(5)
	v_pk_fma_f32 v[42:43], v[42:43], s[6:7], v[34:35] op_sel_hi:[1,0,1]
	v_pk_fma_f32 v[44:45], v[44:45], s[6:7], v[36:37] op_sel_hi:[1,0,1]
	s_waitcnt vmcnt(4)
	v_pk_fma_f32 v[46:47], v[46:47], s[6:7], v[18:19] op_sel_hi:[1,0,1]
	v_pk_fma_f32 v[48:49], v[48:49], s[6:7], v[20:21] op_sel_hi:[1,0,1]
	s_waitcnt vmcnt(3)
	v_pk_fma_f32 v[50:51], v[50:51], s[6:7], v[14:15] op_sel_hi:[1,0,1]
	v_pk_fma_f32 v[52:53], v[52:53], s[6:7], v[16:17] op_sel_hi:[1,0,1]
	s_waitcnt vmcnt(2)
	v_pk_fma_f32 v[54:55], v[54:55], s[6:7], v[10:11] op_sel_hi:[1,0,1]
	v_pk_fma_f32 v[56:57], v[56:57], s[6:7], v[12:13] op_sel_hi:[1,0,1]
	s_waitcnt vmcnt(1)
	v_pk_fma_f32 v[58:59], v[58:59], s[6:7], v[6:7] op_sel_hi:[1,0,1]
	v_pk_fma_f32 v[60:61], v[60:61], s[6:7], v[8:9] op_sel_hi:[1,0,1]
	s_waitcnt vmcnt(0)
	v_pk_fma_f32 v[70:71], v[70:71], s[6:7], v[2:3] op_sel_hi:[1,0,1]
	v_pk_fma_f32 v[72:73], v[72:73], s[6:7], v[4:5] op_sel_hi:[1,0,1]
	global_store_dwordx4 v[160:161], v[120:123], off
	global_store_dwordx4 v[160:161], v[124:127], off offset:64
	global_store_dwordx4 v[160:161], v[128:131], off offset:128
	global_store_dwordx4 v[160:161], v[132:135], off offset:192
	global_store_dwordx4 v[162:163], v[136:139], off
	global_store_dwordx4 v[162:163], v[140:143], off offset:64
	global_store_dwordx4 v[162:163], v[144:147], off offset:128
	global_store_dwordx4 v[162:163], v[148:151], off offset:192
	global_store_dwordx4 v[164:165], v[22:25], off
	global_store_dwordx4 v[164:165], v[26:29], off offset:64
	global_store_dwordx4 v[164:165], v[42:45], off offset:128
	global_store_dwordx4 v[164:165], v[46:49], off offset:192
	global_store_dwordx4 v[166:167], v[50:53], off
	global_store_dwordx4 v[166:167], v[54:57], off offset:64
	global_store_dwordx4 v[166:167], v[58:61], off offset:128
	global_store_dwordx4 v[166:167], v[70:73], off offset:192
	s_add_i32 s7, s7, s3
	s_cmpk_lt_u32 s7, 0x100
	s_cbranch_scc1 .LBB0_422

.Lglds2_14401:
	ds_read_b128 v[152:155], v112 offset:16384
	ds_read_b128 v[156:159], v110
	ds_read_b128 v[160:163], v112 offset:18432
	ds_read_b128 v[164:167], v112 offset:20480
	ds_read_b128 v[168:171], v113 offset:16384
	ds_read_b128 v[172:175], v110 offset:2048
	ds_read_b128 v[204:207], v110 offset:4096
	ds_read_b128 v[208:211], v111
	ds_read_b128 v[212:215], v116 offset:16384
	ds_read_b128 v[216:219], v114
	ds_read_b128 v[220:223], v116 offset:18432
	ds_read_b128 v[224:227], v116 offset:20480
	ds_read_b128 v[228:231], v117 offset:16384
	ds_read_b128 v[232:235], v114 offset:2048
	ds_read_b128 v[236:239], v114 offset:4096
	ds_read_b128 v[240:243], v115
	s_setprio 1
	s_waitcnt lgkmcnt(14)
	v_mfma_i32_16x16x64_i8 v[94:97], v[152:155], v[156:159], v[94:97]
	s_waitcnt lgkmcnt(13)
	v_mfma_i32_16x16x64_i8 v[90:93], v[160:163], v[156:159], v[90:93]
	s_waitcnt lgkmcnt(12)
	v_mfma_i32_16x16x64_i8 v[86:89], v[164:167], v[156:159], v[86:89]
	s_waitcnt lgkmcnt(11)
	v_mfma_i32_16x16x64_i8 v[82:85], v[168:171], v[156:159], v[82:85]
	s_waitcnt lgkmcnt(10)
	v_mfma_i32_16x16x64_i8 v[74:77], v[152:155], v[172:175], v[74:77]
	v_mfma_i32_16x16x64_i8 v[50:53], v[160:163], v[172:175], v[50:53]
	v_mfma_i32_16x16x64_i8 v[38:41], v[164:167], v[172:175], v[38:41]
	v_mfma_i32_16x16x64_i8 v[30:33], v[168:171], v[172:175], v[30:33]
	s_waitcnt lgkmcnt(9)
	v_mfma_i32_16x16x64_i8 v[34:37], v[152:155], v[204:207], v[34:37]
	v_mfma_i32_16x16x64_i8 v[26:29], v[160:163], v[204:207], v[26:29]
	v_mfma_i32_16x16x64_i8 v[22:25], v[164:167], v[204:207], v[22:25]
	v_mfma_i32_16x16x64_i8 v[18:21], v[168:171], v[204:207], v[18:21]
	s_waitcnt lgkmcnt(8)
	v_mfma_i32_16x16x64_i8 v[14:17], v[152:155], v[208:211], v[14:17]
	v_mfma_i32_16x16x64_i8 v[10:13], v[160:163], v[208:211], v[10:13]
	v_mfma_i32_16x16x64_i8 v[6:9], v[164:167], v[208:211], v[6:9]
	v_mfma_i32_16x16x64_i8 v[2:5], v[168:171], v[208:211], v[2:5]
	s_setprio 0
	s_waitcnt lgkmcnt(0)
	s_barrier
	s_add_i32 s4, s13, 0x80
	s_min_u32 s4, s4, 0x1c0
	s_lshl_b32 s4, s4, 1
	s_setprio 1
	v_mfma_i32_16x16x64_i8 v[94:97], v[212:215], v[216:219], v[94:97]
	s_add_u32 m0, s14, 0x0
	v_lshl_add_u64 v[200:201], v[184:185], 0, s[4:5]
	global_load_lds_dwordx4 v[200:201], off
	v_mfma_i32_16x16x64_i8 v[90:93], v[220:223], v[216:219], v[90:93]
	v_mfma_i32_16x16x64_i8 v[86:89], v[224:227], v[216:219], v[86:89]
	s_add_u32 m0, s14, 0x1000
	v_lshl_add_u64 v[202:203], v[186:187], 0, s[4:5]
	global_load_lds_dwordx4 v[202:203], off
	v_mfma_i32_16x16x64_i8 v[82:85], v[228:231], v[216:219], v[82:85]
	v_mfma_i32_16x16x64_i8 v[74:77], v[212:215], v[232:235], v[74:77]
	s_add_u32 m0, s14, 0x2000
	v_lshl_add_u64 v[200:201], v[188:189], 0, s[4:5]
	global_load_lds_dwordx4 v[200:201], off
	v_mfma_i32_16x16x64_i8 v[50:53], v[220:223], v[232:235], v[50:53]
	v_mfma_i32_16x16x64_i8 v[38:41], v[224:227], v[232:235], v[38:41]
	s_add_u32 m0, s14, 0x3000
	v_lshl_add_u64 v[202:203], v[190:191], 0, s[4:5]
	global_load_lds_dwordx4 v[202:203], off
	v_mfma_i32_16x16x64_i8 v[30:33], v[228:231], v[232:235], v[30:33]
	v_mfma_i32_16x16x64_i8 v[34:37], v[212:215], v[236:239], v[34:37]
	s_add_u32 m0, s14, 0x4000
	v_lshl_add_u64 v[200:201], v[192:193], 0, s[4:5]
	global_load_lds_dwordx4 v[200:201], off
	v_mfma_i32_16x16x64_i8 v[26:29], v[220:223], v[236:239], v[26:29]
	v_mfma_i32_16x16x64_i8 v[22:25], v[224:227], v[236:239], v[22:25]
	s_add_u32 m0, s14, 0x5000
	v_lshl_add_u64 v[202:203], v[194:195], 0, s[4:5]
	global_load_lds_dwordx4 v[202:203], off
	v_mfma_i32_16x16x64_i8 v[18:21], v[228:231], v[236:239], v[18:21]
	v_mfma_i32_16x16x64_i8 v[14:17], v[212:215], v[240:243], v[14:17]
	s_add_u32 m0, s14, 0x6000
	v_lshl_add_u64 v[200:201], v[196:197], 0, s[4:5]
	global_load_lds_dwordx4 v[200:201], off
	v_mfma_i32_16x16x64_i8 v[10:13], v[220:223], v[240:243], v[10:13]
	v_mfma_i32_16x16x64_i8 v[6:9], v[224:227], v[240:243], v[6:9]
	s_add_u32 m0, s14, 0x7000
	v_lshl_add_u64 v[202:203], v[198:199], 0, s[4:5]
	global_load_lds_dwordx4 v[202:203], off
	v_mfma_i32_16x16x64_i8 v[2:5], v[228:231], v[240:243], v[2:5]
	s_setprio 0
	s_waitcnt vmcnt(8)
	s_barrier
	ds_read_b128 v[152:155], v112 offset:49152
	ds_read_b128 v[156:159], v110 offset:32768
	ds_read_b128 v[160:163], v112 offset:51200
	ds_read_b128 v[164:167], v112 offset:53248
	ds_read_b128 v[168:171], v113 offset:49152
	ds_read_b128 v[172:175], v110 offset:34816
	ds_read_b128 v[204:207], v110 offset:36864
	ds_read_b128 v[208:211], v111 offset:32768
	ds_read_b128 v[212:215], v116 offset:49152
	ds_read_b128 v[216:219], v114 offset:32768
	ds_read_b128 v[220:223], v116 offset:51200
	ds_read_b128 v[224:227], v116 offset:53248
	ds_read_b128 v[228:231], v117 offset:49152
	ds_read_b128 v[232:235], v114 offset:34816
	ds_read_b128 v[236:239], v114 offset:36864
	ds_read_b128 v[240:243], v115 offset:32768
	s_setprio 1
	s_waitcnt lgkmcnt(14)
	v_mfma_i32_16x16x64_i8 v[94:97], v[152:155], v[156:159], v[94:97]
	s_waitcnt lgkmcnt(13)
	v_mfma_i32_16x16x64_i8 v[90:93], v[160:163], v[156:159], v[90:93]
	s_waitcnt lgkmcnt(12)
	v_mfma_i32_16x16x64_i8 v[86:89], v[164:167], v[156:159], v[86:89]
	s_waitcnt lgkmcnt(11)
	v_mfma_i32_16x16x64_i8 v[82:85], v[168:171], v[156:159], v[82:85]
	s_waitcnt lgkmcnt(10)
	v_mfma_i32_16x16x64_i8 v[74:77], v[152:155], v[172:175], v[74:77]
	v_mfma_i32_16x16x64_i8 v[50:53], v[160:163], v[172:175], v[50:53]
	v_mfma_i32_16x16x64_i8 v[38:41], v[164:167], v[172:175], v[38:41]
	v_mfma_i32_16x16x64_i8 v[30:33], v[168:171], v[172:175], v[30:33]
	s_waitcnt lgkmcnt(9)
	v_mfma_i32_16x16x64_i8 v[34:37], v[152:155], v[204:207], v[34:37]
	v_mfma_i32_16x16x64_i8 v[26:29], v[160:163], v[204:207], v[26:29]
	v_mfma_i32_16x16x64_i8 v[22:25], v[164:167], v[204:207], v[22:25]
	v_mfma_i32_16x16x64_i8 v[18:21], v[168:171], v[204:207], v[18:21]
	s_waitcnt lgkmcnt(8)
	v_mfma_i32_16x16x64_i8 v[14:17], v[152:155], v[208:211], v[14:17]
	v_mfma_i32_16x16x64_i8 v[10:13], v[160:163], v[208:211], v[10:13]
	v_mfma_i32_16x16x64_i8 v[6:9], v[164:167], v[208:211], v[6:9]
	v_mfma_i32_16x16x64_i8 v[2:5], v[168:171], v[208:211], v[2:5]
	s_setprio 0
	s_waitcnt lgkmcnt(0)
	s_barrier
	s_add_i32 s4, s13, 0xc0
	s_min_u32 s4, s4, 0x1c0
	s_lshl_b32 s4, s4, 1
	s_setprio 1
	v_mfma_i32_16x16x64_i8 v[94:97], v[212:215], v[216:219], v[94:97]
	s_add_u32 m0, s14, 0x8000
	v_lshl_add_u64 v[200:201], v[184:185], 0, s[4:5]
	global_load_lds_dwordx4 v[200:201], off
	v_mfma_i32_16x16x64_i8 v[90:93], v[220:223], v[216:219], v[90:93]
	v_mfma_i32_16x16x64_i8 v[86:89], v[224:227], v[216:219], v[86:89]
	s_add_u32 m0, s14, 0x9000
	v_lshl_add_u64 v[202:203], v[186:187], 0, s[4:5]
	global_load_lds_dwordx4 v[202:203], off
	v_mfma_i32_16x16x64_i8 v[82:85], v[228:231], v[216:219], v[82:85]
	v_mfma_i32_16x16x64_i8 v[74:77], v[212:215], v[232:235], v[74:77]
	s_add_u32 m0, s14, 0xa000
	v_lshl_add_u64 v[200:201], v[188:189], 0, s[4:5]
	global_load_lds_dwordx4 v[200:201], off
	v_mfma_i32_16x16x64_i8 v[50:53], v[220:223], v[232:235], v[50:53]
	v_mfma_i32_16x16x64_i8 v[38:41], v[224:227], v[232:235], v[38:41]
	s_add_u32 m0, s14, 0xb000
	v_lshl_add_u64 v[202:203], v[190:191], 0, s[4:5]
	global_load_lds_dwordx4 v[202:203], off
	v_mfma_i32_16x16x64_i8 v[30:33], v[228:231], v[232:235], v[30:33]
	v_mfma_i32_16x16x64_i8 v[34:37], v[212:215], v[236:239], v[34:37]
	s_add_u32 m0, s14, 0xc000
	v_lshl_add_u64 v[200:201], v[192:193], 0, s[4:5]
	global_load_lds_dwordx4 v[200:201], off
	v_mfma_i32_16x16x64_i8 v[26:29], v[220:223], v[236:239], v[26:29]
	v_mfma_i32_16x16x64_i8 v[22:25], v[224:227], v[236:239], v[22:25]
	s_add_u32 m0, s14, 0xd000
	v_lshl_add_u64 v[202:203], v[194:195], 0, s[4:5]
	global_load_lds_dwordx4 v[202:203], off
	v_mfma_i32_16x16x64_i8 v[18:21], v[228:231], v[236:239], v[18:21]
	v_mfma_i32_16x16x64_i8 v[14:17], v[212:215], v[240:243], v[14:17]
	s_add_u32 m0, s14, 0xe000
	v_lshl_add_u64 v[200:201], v[196:197], 0, s[4:5]
	global_load_lds_dwordx4 v[200:201], off
	v_mfma_i32_16x16x64_i8 v[10:13], v[220:223], v[240:243], v[10:13]
	v_mfma_i32_16x16x64_i8 v[6:9], v[224:227], v[240:243], v[6:9]
	s_add_u32 m0, s14, 0xf000
	v_lshl_add_u64 v[202:203], v[198:199], 0, s[4:5]
	global_load_lds_dwordx4 v[202:203], off
	v_mfma_i32_16x16x64_i8 v[2:5], v[228:231], v[240:243], v[2:5]
	s_setprio 0
	s_waitcnt vmcnt(8)
	s_barrier
	s_add_i32 s13, s13, 0x80
	s_add_i32 s12, s12, 2
	s_cmp_lt_u32 s12, 6
	s_cbranch_scc1 .Lglds2_14401
	s_waitcnt vmcnt(0)
	v_cvt_f32_i32_e32 v94, v94
	v_cvt_f32_i32_e32 v95, v95
	v_cvt_f32_i32_e32 v96, v96
	v_cvt_f32_i32_e32 v97, v97
	v_cvt_f32_i32_e32 v90, v90
	v_cvt_f32_i32_e32 v91, v91
	v_cvt_f32_i32_e32 v92, v92
	v_cvt_f32_i32_e32 v93, v93
	v_cvt_f32_i32_e32 v86, v86
	v_cvt_f32_i32_e32 v87, v87
	v_cvt_f32_i32_e32 v88, v88
	v_cvt_f32_i32_e32 v89, v89
	v_cvt_f32_i32_e32 v82, v82
	v_cvt_f32_i32_e32 v83, v83
	v_cvt_f32_i32_e32 v84, v84
	v_cvt_f32_i32_e32 v85, v85
	v_cvt_f32_i32_e32 v74, v74
	v_cvt_f32_i32_e32 v75, v75
	v_cvt_f32_i32_e32 v76, v76
	v_cvt_f32_i32_e32 v77, v77
	v_cvt_f32_i32_e32 v50, v50
	v_cvt_f32_i32_e32 v51, v51
	v_cvt_f32_i32_e32 v52, v52
	v_cvt_f32_i32_e32 v53, v53
	v_cvt_f32_i32_e32 v38, v38
	v_cvt_f32_i32_e32 v39, v39
	v_cvt_f32_i32_e32 v40, v40
	v_cvt_f32_i32_e32 v41, v41
	v_cvt_f32_i32_e32 v30, v30
	v_cvt_f32_i32_e32 v31, v31
	v_cvt_f32_i32_e32 v32, v32
	v_cvt_f32_i32_e32 v33, v33
	v_cvt_f32_i32_e32 v34, v34
	v_cvt_f32_i32_e32 v35, v35
	v_cvt_f32_i32_e32 v36, v36
	v_cvt_f32_i32_e32 v37, v37
	v_cvt_f32_i32_e32 v26, v26
	v_cvt_f32_i32_e32 v27, v27
	v_cvt_f32_i32_e32 v28, v28
	v_cvt_f32_i32_e32 v29, v29
	v_cvt_f32_i32_e32 v22, v22
	v_cvt_f32_i32_e32 v23, v23
	v_cvt_f32_i32_e32 v24, v24
	v_cvt_f32_i32_e32 v25, v25
	v_cvt_f32_i32_e32 v18, v18
	v_cvt_f32_i32_e32 v19, v19
	v_cvt_f32_i32_e32 v20, v20
	v_cvt_f32_i32_e32 v21, v21
	v_cvt_f32_i32_e32 v14, v14
	v_cvt_f32_i32_e32 v15, v15
	v_cvt_f32_i32_e32 v16, v16
	v_cvt_f32_i32_e32 v17, v17
	v_cvt_f32_i32_e32 v10, v10
	v_cvt_f32_i32_e32 v11, v11
	v_cvt_f32_i32_e32 v12, v12
	v_cvt_f32_i32_e32 v13, v13
	v_cvt_f32_i32_e32 v6, v6
	v_cvt_f32_i32_e32 v7, v7
	v_cvt_f32_i32_e32 v8, v8
	v_cvt_f32_i32_e32 v9, v9
	v_cvt_f32_i32_e32 v2, v2
	v_cvt_f32_i32_e32 v3, v3
	v_cvt_f32_i32_e32 v4, v4
	v_cvt_f32_i32_e32 v5, v5
	s_waitcnt vmcnt(0)
	v_add_u32_e32 v98, s10, v118
	v_or_b32_e32 v146, s11, v119
	v_lshl_add_u64 v[144:145], v[98:99], 2, s[68:69]
	v_lshlrev_b32_e32 v148, 2, v146
	global_load_dword v136, v[144:145], off
	global_load_dword v138, v[144:145], off offset:64
	global_load_dword v140, v[144:145], off offset:128
	global_load_dword v142, v[144:145], off offset:192
	global_load_dwordx4 v[120:123], v148, s[74:75]
	global_load_dwordx4 v[124:127], v148, s[74:75] offset:64
	global_load_dwordx4 v[128:131], v148, s[74:75] offset:128
	global_load_dwordx4 v[132:135], v148, s[74:75] offset:192
	v_lshlrev_b32_e32 v146, 1, v146
	v_mov_b32_e32 v147, v99
	v_lshlrev_b64 v[42:43], 12, v[98:99]
	v_lshl_add_u64 v[42:43], s[64:65], 0, v[42:43]
	v_lshl_add_u64 v[42:43], v[42:43], 0, v[146:147]
	v_or_b32_e32 v54, 16, v98
	v_mov_b32_e32 v55, v99
	v_lshlrev_b64 v[44:45], 12, v[54:55]
	v_lshl_add_u64 v[44:45], s[64:65], 0, v[44:45]
	v_lshl_add_u64 v[44:45], v[44:45], 0, v[146:147]
	v_or_b32_e32 v54, 32, v98
	v_mov_b32_e32 v55, v99
	v_lshlrev_b64 v[46:47], 12, v[54:55]
	v_lshl_add_u64 v[46:47], s[64:65], 0, v[46:47]
	v_lshl_add_u64 v[46:47], v[46:47], 0, v[146:147]
	v_or_b32_e32 v54, 48, v98
	v_mov_b32_e32 v55, v99
	v_lshlrev_b64 v[48:49], 12, v[54:55]
	v_lshl_add_u64 v[48:49], s[64:65], 0, v[48:49]
	v_lshl_add_u64 v[48:49], v[48:49], 0, v[146:147]
	s_waitcnt vmcnt(0)
	v_pk_mul_f32 v[94:95], v[136:137], v[94:95] op_sel_hi:[0,1]
	v_pk_mul_f32 v[96:97], v[136:137], v[96:97] op_sel_hi:[0,1]
	v_pk_mul_f32 v[94:95], v[120:121], v[94:95]
	v_pk_mul_f32 v[96:97], v[96:97], v[122:123]
	v_cvt_pk_bf16_f32 v94, v94, v95
	v_cvt_pk_bf16_f32 v95, v96, v97
	global_store_dwordx2 v[42:43], v[94:95], off
	v_pk_mul_f32 v[90:91], v[136:137], v[90:91] op_sel_hi:[0,1]
	v_pk_mul_f32 v[92:93], v[136:137], v[92:93] op_sel_hi:[0,1]
	v_pk_mul_f32 v[90:91], v[124:125], v[90:91]
	v_pk_mul_f32 v[92:93], v[92:93], v[126:127]
	v_cvt_pk_bf16_f32 v90, v90, v91
	v_cvt_pk_bf16_f32 v91, v92, v93
	global_store_dwordx2 v[42:43], v[90:91], off offset:32
	v_pk_mul_f32 v[86:87], v[136:137], v[86:87] op_sel_hi:[0,1]
	v_pk_mul_f32 v[88:89], v[136:137], v[88:89] op_sel_hi:[0,1]
	v_pk_mul_f32 v[86:87], v[128:129], v[86:87]
	v_pk_mul_f32 v[88:89], v[88:89], v[130:131]
	v_cvt_pk_bf16_f32 v86, v86, v87
	v_cvt_pk_bf16_f32 v87, v88, v89
	global_store_dwordx2 v[42:43], v[86:87], off offset:64
	v_pk_mul_f32 v[82:83], v[136:137], v[82:83] op_sel_hi:[0,1]
	v_pk_mul_f32 v[84:85], v[136:137], v[84:85] op_sel_hi:[0,1]
	v_pk_mul_f32 v[82:83], v[132:133], v[82:83]
	v_pk_mul_f32 v[84:85], v[84:85], v[134:135]
	v_cvt_pk_bf16_f32 v82, v82, v83
	v_cvt_pk_bf16_f32 v83, v84, v85
	global_store_dwordx2 v[42:43], v[82:83], off offset:96
	v_pk_mul_f32 v[74:75], v[138:139], v[74:75] op_sel_hi:[0,1]
	v_pk_mul_f32 v[76:77], v[138:139], v[76:77] op_sel_hi:[0,1]
	v_pk_mul_f32 v[74:75], v[120:121], v[74:75]
	v_pk_mul_f32 v[76:77], v[76:77], v[122:123]
	v_cvt_pk_bf16_f32 v74, v74, v75
	v_cvt_pk_bf16_f32 v75, v76, v77
	global_store_dwordx2 v[44:45], v[74:75], off
	v_pk_mul_f32 v[50:51], v[138:139], v[50:51] op_sel_hi:[0,1]
	v_pk_mul_f32 v[52:53], v[138:139], v[52:53] op_sel_hi:[0,1]
	v_pk_mul_f32 v[50:51], v[124:125], v[50:51]
	v_pk_mul_f32 v[52:53], v[52:53], v[126:127]
	v_cvt_pk_bf16_f32 v50, v50, v51
	v_cvt_pk_bf16_f32 v51, v52, v53
	global_store_dwordx2 v[44:45], v[50:51], off offset:32
	v_pk_mul_f32 v[38:39], v[138:139], v[38:39] op_sel_hi:[0,1]
	v_pk_mul_f32 v[40:41], v[138:139], v[40:41] op_sel_hi:[0,1]
	v_pk_mul_f32 v[38:39], v[128:129], v[38:39]
	v_pk_mul_f32 v[40:41], v[40:41], v[130:131]
	v_cvt_pk_bf16_f32 v38, v38, v39
	v_cvt_pk_bf16_f32 v39, v40, v41
	global_store_dwordx2 v[44:45], v[38:39], off offset:64
	v_pk_mul_f32 v[30:31], v[138:139], v[30:31] op_sel_hi:[0,1]
	v_pk_mul_f32 v[32:33], v[138:139], v[32:33] op_sel_hi:[0,1]
	v_pk_mul_f32 v[30:31], v[132:133], v[30:31]
	v_pk_mul_f32 v[32:33], v[32:33], v[134:135]
	v_cvt_pk_bf16_f32 v30, v30, v31
	v_cvt_pk_bf16_f32 v31, v32, v33
	global_store_dwordx2 v[44:45], v[30:31], off offset:96
	v_pk_mul_f32 v[34:35], v[140:141], v[34:35] op_sel_hi:[0,1]
	v_pk_mul_f32 v[36:37], v[140:141], v[36:37] op_sel_hi:[0,1]
	v_pk_mul_f32 v[34:35], v[120:121], v[34:35]
	v_pk_mul_f32 v[36:37], v[36:37], v[122:123]
	v_cvt_pk_bf16_f32 v34, v34, v35
	v_cvt_pk_bf16_f32 v35, v36, v37
	global_store_dwordx2 v[46:47], v[34:35], off
	v_pk_mul_f32 v[26:27], v[140:141], v[26:27] op_sel_hi:[0,1]
	v_pk_mul_f32 v[28:29], v[140:141], v[28:29] op_sel_hi:[0,1]
	v_pk_mul_f32 v[26:27], v[124:125], v[26:27]
	v_pk_mul_f32 v[28:29], v[28:29], v[126:127]
	v_cvt_pk_bf16_f32 v26, v26, v27
	v_cvt_pk_bf16_f32 v27, v28, v29
	global_store_dwordx2 v[46:47], v[26:27], off offset:32
	v_pk_mul_f32 v[22:23], v[140:141], v[22:23] op_sel_hi:[0,1]
	v_pk_mul_f32 v[24:25], v[140:141], v[24:25] op_sel_hi:[0,1]
	v_pk_mul_f32 v[22:23], v[128:129], v[22:23]
	v_pk_mul_f32 v[24:25], v[24:25], v[130:131]
	v_cvt_pk_bf16_f32 v22, v22, v23
	v_cvt_pk_bf16_f32 v23, v24, v25
	global_store_dwordx2 v[46:47], v[22:23], off offset:64
	v_pk_mul_f32 v[18:19], v[140:141], v[18:19] op_sel_hi:[0,1]
	v_pk_mul_f32 v[20:21], v[140:141], v[20:21] op_sel_hi:[0,1]
	v_pk_mul_f32 v[18:19], v[132:133], v[18:19]
	v_pk_mul_f32 v[20:21], v[20:21], v[134:135]
	v_cvt_pk_bf16_f32 v18, v18, v19
	v_cvt_pk_bf16_f32 v19, v20, v21
	global_store_dwordx2 v[46:47], v[18:19], off offset:96
	v_pk_mul_f32 v[14:15], v[142:143], v[14:15] op_sel_hi:[0,1]
	v_pk_mul_f32 v[16:17], v[142:143], v[16:17] op_sel_hi:[0,1]
	v_pk_mul_f32 v[14:15], v[120:121], v[14:15]
	v_pk_mul_f32 v[16:17], v[16:17], v[122:123]
	v_cvt_pk_bf16_f32 v14, v14, v15
	v_cvt_pk_bf16_f32 v15, v16, v17
	global_store_dwordx2 v[48:49], v[14:15], off
	v_pk_mul_f32 v[10:11], v[142:143], v[10:11] op_sel_hi:[0,1]
	v_pk_mul_f32 v[12:13], v[142:143], v[12:13] op_sel_hi:[0,1]
	v_pk_mul_f32 v[10:11], v[124:125], v[10:11]
	v_pk_mul_f32 v[12:13], v[12:13], v[126:127]
	v_cvt_pk_bf16_f32 v10, v10, v11
	v_cvt_pk_bf16_f32 v11, v12, v13
	global_store_dwordx2 v[48:49], v[10:11], off offset:32
	v_pk_mul_f32 v[6:7], v[142:143], v[6:7] op_sel_hi:[0,1]
	v_pk_mul_f32 v[8:9], v[142:143], v[8:9] op_sel_hi:[0,1]
	v_pk_mul_f32 v[6:7], v[128:129], v[6:7]
	v_pk_mul_f32 v[8:9], v[8:9], v[130:131]
	v_cvt_pk_bf16_f32 v6, v6, v7
	v_cvt_pk_bf16_f32 v7, v8, v9
	global_store_dwordx2 v[48:49], v[6:7], off offset:64
	v_pk_mul_f32 v[2:3], v[142:143], v[2:3] op_sel_hi:[0,1]
	v_pk_mul_f32 v[4:5], v[142:143], v[4:5] op_sel_hi:[0,1]
	v_pk_mul_f32 v[2:3], v[132:133], v[2:3]
	v_pk_mul_f32 v[4:5], v[4:5], v[134:135]
	v_cvt_pk_bf16_f32 v2, v2, v3
	v_cvt_pk_bf16_f32 v3, v4, v5
	global_store_dwordx2 v[48:49], v[2:3], off offset:96
	s_add_i32 s6, s6, s3
	s_cmpk_lt_u32 s6, 0x200
	s_cbranch_scc1 .LBB0_518

.Lglds2_22142:
	ds_read_b128 v[152:155], v112 offset:16384
	ds_read_b128 v[156:159], v110
	ds_read_b128 v[160:163], v112 offset:18432
	ds_read_b128 v[164:167], v112 offset:20480
	ds_read_b128 v[168:171], v113 offset:16384
	ds_read_b128 v[172:175], v110 offset:2048
	ds_read_b128 v[208:211], v110 offset:4096
	ds_read_b128 v[212:215], v111
	ds_read_b128 v[216:219], v116 offset:16384
	ds_read_b128 v[220:223], v114
	ds_read_b128 v[224:227], v116 offset:18432
	ds_read_b128 v[228:231], v116 offset:20480
	ds_read_b128 v[232:235], v117 offset:16384
	ds_read_b128 v[236:239], v114 offset:2048
	ds_read_b128 v[240:243], v114 offset:4096
	ds_read_b128 v[244:247], v115
	s_setprio 1
	s_waitcnt lgkmcnt(14)
	v_mfma_f32_16x16x32_bf16 v[94:97], v[152:155], v[156:159], v[94:97]
	s_waitcnt lgkmcnt(13)
	v_mfma_f32_16x16x32_bf16 v[90:93], v[160:163], v[156:159], v[90:93]
	s_waitcnt lgkmcnt(12)
	v_mfma_f32_16x16x32_bf16 v[86:89], v[164:167], v[156:159], v[86:89]
	s_waitcnt lgkmcnt(11)
	v_mfma_f32_16x16x32_bf16 v[82:85], v[168:171], v[156:159], v[82:85]
	s_waitcnt lgkmcnt(10)
	v_mfma_f32_16x16x32_bf16 v[54:57], v[152:155], v[172:175], v[54:57]
	v_mfma_f32_16x16x32_bf16 v[42:45], v[160:163], v[172:175], v[42:45]
	v_mfma_f32_16x16x32_bf16 v[38:41], v[164:167], v[172:175], v[38:41]
	v_mfma_f32_16x16x32_bf16 v[34:37], v[168:171], v[172:175], v[34:37]
	s_waitcnt lgkmcnt(9)
	v_mfma_f32_16x16x32_bf16 v[78:81], v[152:155], v[208:211], v[78:81]
	v_mfma_f32_16x16x32_bf16 v[74:77], v[160:163], v[208:211], v[74:77]
	v_mfma_f32_16x16x32_bf16 v[70:73], v[164:167], v[208:211], v[70:73]
	v_mfma_f32_16x16x32_bf16 v[66:69], v[168:171], v[208:211], v[66:69]
	s_waitcnt lgkmcnt(8)
	v_mfma_f32_16x16x32_bf16 v[62:65], v[152:155], v[212:215], v[62:65]
	v_mfma_f32_16x16x32_bf16 v[58:61], v[160:163], v[212:215], v[58:61]
	v_mfma_f32_16x16x32_bf16 v[50:53], v[164:167], v[212:215], v[50:53]
	v_mfma_f32_16x16x32_bf16 v[46:49], v[168:171], v[212:215], v[46:49]
	s_setprio 0
	s_waitcnt lgkmcnt(0)
	s_barrier
	s_add_i32 s4, s16, 0x80
	s_min_u32 s4, s4, 0x3c0
	s_lshl_b32 s4, s4, 1
	s_setprio 1
	v_mfma_f32_16x16x32_bf16 v[94:97], v[216:219], v[220:223], v[94:97]
	s_add_u32 m0, s17, 0x0
	v_lshl_add_u64 v[204:205], v[188:189], 0, s[4:5]
	global_load_lds_dwordx4 v[204:205], off
	v_mfma_f32_16x16x32_bf16 v[90:93], v[224:227], v[220:223], v[90:93]
	v_mfma_f32_16x16x32_bf16 v[86:89], v[228:231], v[220:223], v[86:89]
	s_add_u32 m0, s17, 0x1000
	v_lshl_add_u64 v[206:207], v[190:191], 0, s[4:5]
	global_load_lds_dwordx4 v[206:207], off
	v_mfma_f32_16x16x32_bf16 v[82:85], v[232:235], v[220:223], v[82:85]
	v_mfma_f32_16x16x32_bf16 v[54:57], v[216:219], v[236:239], v[54:57]
	s_add_u32 m0, s17, 0x2000
	v_lshl_add_u64 v[204:205], v[192:193], 0, s[4:5]
	global_load_lds_dwordx4 v[204:205], off
	v_mfma_f32_16x16x32_bf16 v[42:45], v[224:227], v[236:239], v[42:45]
	v_mfma_f32_16x16x32_bf16 v[38:41], v[228:231], v[236:239], v[38:41]
	s_add_u32 m0, s17, 0x3000
	v_lshl_add_u64 v[206:207], v[194:195], 0, s[4:5]
	global_load_lds_dwordx4 v[206:207], off
	v_mfma_f32_16x16x32_bf16 v[34:37], v[232:235], v[236:239], v[34:37]
	v_mfma_f32_16x16x32_bf16 v[78:81], v[216:219], v[240:243], v[78:81]
	s_add_u32 m0, s17, 0x4000
	v_lshl_add_u64 v[204:205], v[196:197], 0, s[4:5]
	global_load_lds_dwordx4 v[204:205], off
	v_mfma_f32_16x16x32_bf16 v[74:77], v[224:227], v[240:243], v[74:77]
	v_mfma_f32_16x16x32_bf16 v[70:73], v[228:231], v[240:243], v[70:73]
	s_add_u32 m0, s17, 0x5000
	v_lshl_add_u64 v[206:207], v[198:199], 0, s[4:5]
	global_load_lds_dwordx4 v[206:207], off
	v_mfma_f32_16x16x32_bf16 v[66:69], v[232:235], v[240:243], v[66:69]
	v_mfma_f32_16x16x32_bf16 v[62:65], v[216:219], v[244:247], v[62:65]
	s_add_u32 m0, s17, 0x6000
	v_lshl_add_u64 v[204:205], v[200:201], 0, s[4:5]
	global_load_lds_dwordx4 v[204:205], off
	v_mfma_f32_16x16x32_bf16 v[58:61], v[224:227], v[244:247], v[58:61]
	v_mfma_f32_16x16x32_bf16 v[50:53], v[228:231], v[244:247], v[50:53]
	s_add_u32 m0, s17, 0x7000
	v_lshl_add_u64 v[206:207], v[202:203], 0, s[4:5]
	global_load_lds_dwordx4 v[206:207], off
	v_mfma_f32_16x16x32_bf16 v[46:49], v[232:235], v[244:247], v[46:49]
	s_setprio 0
	s_waitcnt vmcnt(8)
	s_barrier
	ds_read_b128 v[152:155], v112 offset:49152
	ds_read_b128 v[156:159], v110 offset:32768
	ds_read_b128 v[160:163], v112 offset:51200
	ds_read_b128 v[164:167], v112 offset:53248
	ds_read_b128 v[168:171], v113 offset:49152
	ds_read_b128 v[172:175], v110 offset:34816
	ds_read_b128 v[208:211], v110 offset:36864
	ds_read_b128 v[212:215], v111 offset:32768
	ds_read_b128 v[216:219], v116 offset:49152
	ds_read_b128 v[220:223], v114 offset:32768
	ds_read_b128 v[224:227], v116 offset:51200
	ds_read_b128 v[228:231], v116 offset:53248
	ds_read_b128 v[232:235], v117 offset:49152
	ds_read_b128 v[236:239], v114 offset:34816
	ds_read_b128 v[240:243], v114 offset:36864
	ds_read_b128 v[244:247], v115 offset:32768
	s_setprio 1
	s_waitcnt lgkmcnt(14)
	v_mfma_f32_16x16x32_bf16 v[94:97], v[152:155], v[156:159], v[94:97]
	s_waitcnt lgkmcnt(13)
	v_mfma_f32_16x16x32_bf16 v[90:93], v[160:163], v[156:159], v[90:93]
	s_waitcnt lgkmcnt(12)
	v_mfma_f32_16x16x32_bf16 v[86:89], v[164:167], v[156:159], v[86:89]
	s_waitcnt lgkmcnt(11)
	v_mfma_f32_16x16x32_bf16 v[82:85], v[168:171], v[156:159], v[82:85]
	s_waitcnt lgkmcnt(10)
	v_mfma_f32_16x16x32_bf16 v[54:57], v[152:155], v[172:175], v[54:57]
	v_mfma_f32_16x16x32_bf16 v[42:45], v[160:163], v[172:175], v[42:45]
	v_mfma_f32_16x16x32_bf16 v[38:41], v[164:167], v[172:175], v[38:41]
	v_mfma_f32_16x16x32_bf16 v[34:37], v[168:171], v[172:175], v[34:37]
	s_waitcnt lgkmcnt(9)
	v_mfma_f32_16x16x32_bf16 v[78:81], v[152:155], v[208:211], v[78:81]
	v_mfma_f32_16x16x32_bf16 v[74:77], v[160:163], v[208:211], v[74:77]
	v_mfma_f32_16x16x32_bf16 v[70:73], v[164:167], v[208:211], v[70:73]
	v_mfma_f32_16x16x32_bf16 v[66:69], v[168:171], v[208:211], v[66:69]
	s_waitcnt lgkmcnt(8)
	v_mfma_f32_16x16x32_bf16 v[62:65], v[152:155], v[212:215], v[62:65]
	v_mfma_f32_16x16x32_bf16 v[58:61], v[160:163], v[212:215], v[58:61]
	v_mfma_f32_16x16x32_bf16 v[50:53], v[164:167], v[212:215], v[50:53]
	v_mfma_f32_16x16x32_bf16 v[46:49], v[168:171], v[212:215], v[46:49]
	s_setprio 0
	s_waitcnt lgkmcnt(0)
	s_barrier
	s_add_i32 s4, s16, 0xc0
	s_min_u32 s4, s4, 0x3c0
	s_lshl_b32 s4, s4, 1
	s_setprio 1
	v_mfma_f32_16x16x32_bf16 v[94:97], v[216:219], v[220:223], v[94:97]
	s_add_u32 m0, s17, 0x8000
	v_lshl_add_u64 v[204:205], v[188:189], 0, s[4:5]
	global_load_lds_dwordx4 v[204:205], off
	v_mfma_f32_16x16x32_bf16 v[90:93], v[224:227], v[220:223], v[90:93]
	v_mfma_f32_16x16x32_bf16 v[86:89], v[228:231], v[220:223], v[86:89]
	s_add_u32 m0, s17, 0x9000
	v_lshl_add_u64 v[206:207], v[190:191], 0, s[4:5]
	global_load_lds_dwordx4 v[206:207], off
	v_mfma_f32_16x16x32_bf16 v[82:85], v[232:235], v[220:223], v[82:85]
	v_mfma_f32_16x16x32_bf16 v[54:57], v[216:219], v[236:239], v[54:57]
	s_add_u32 m0, s17, 0xa000
	v_lshl_add_u64 v[204:205], v[192:193], 0, s[4:5]
	global_load_lds_dwordx4 v[204:205], off
	v_mfma_f32_16x16x32_bf16 v[42:45], v[224:227], v[236:239], v[42:45]
	v_mfma_f32_16x16x32_bf16 v[38:41], v[228:231], v[236:239], v[38:41]
	s_add_u32 m0, s17, 0xb000
	v_lshl_add_u64 v[206:207], v[194:195], 0, s[4:5]
	global_load_lds_dwordx4 v[206:207], off
	v_mfma_f32_16x16x32_bf16 v[34:37], v[232:235], v[236:239], v[34:37]
	v_mfma_f32_16x16x32_bf16 v[78:81], v[216:219], v[240:243], v[78:81]
	s_add_u32 m0, s17, 0xc000
	v_lshl_add_u64 v[204:205], v[196:197], 0, s[4:5]
	global_load_lds_dwordx4 v[204:205], off
	v_mfma_f32_16x16x32_bf16 v[74:77], v[224:227], v[240:243], v[74:77]
	v_mfma_f32_16x16x32_bf16 v[70:73], v[228:231], v[240:243], v[70:73]
	s_add_u32 m0, s17, 0xd000
	v_lshl_add_u64 v[206:207], v[198:199], 0, s[4:5]
	global_load_lds_dwordx4 v[206:207], off
	v_mfma_f32_16x16x32_bf16 v[66:69], v[232:235], v[240:243], v[66:69]
	v_mfma_f32_16x16x32_bf16 v[62:65], v[216:219], v[244:247], v[62:65]
	s_add_u32 m0, s17, 0xe000
	v_lshl_add_u64 v[204:205], v[200:201], 0, s[4:5]
	global_load_lds_dwordx4 v[204:205], off
	v_mfma_f32_16x16x32_bf16 v[58:61], v[224:227], v[244:247], v[58:61]
	v_mfma_f32_16x16x32_bf16 v[50:53], v[228:231], v[244:247], v[50:53]
	s_add_u32 m0, s17, 0xf000
	v_lshl_add_u64 v[206:207], v[202:203], 0, s[4:5]
	global_load_lds_dwordx4 v[206:207], off
	v_mfma_f32_16x16x32_bf16 v[46:49], v[232:235], v[244:247], v[46:49]
	s_setprio 0
	s_waitcnt vmcnt(8)
	s_barrier
	s_add_i32 s16, s16, 0x80
	s_add_i32 s15, s15, 2
	s_cmp_lt_u32 s15, 14
	s_cbranch_scc1 .Lglds2_22142
	s_waitcnt vmcnt(0)
	s_waitcnt vmcnt(7)
	v_or_b32_e32 v2, s14, v119
	s_waitcnt vmcnt(5)
	v_add_u32_e32 v10, s13, v118
	v_mov_b64_e32 v[4:5], s[64:65]
	v_ashrrev_i32_e32 v3, 31, v2
	v_mad_i64_i32 v[6:7], s[14:15], v10, s12, v[4:5]
	v_lshlrev_b64 v[2:3], 1, v[2:3]
	v_lshl_add_u64 v[6:7], v[6:7], 0, v[2:3]
	v_cvt_pk_bf16_f32 v8, v94, v95
	v_cvt_pk_bf16_f32 v9, v96, v97
	global_store_dwordx2 v[6:7], v[8:9], off
	v_cvt_pk_bf16_f32 v8, v90, v91
	v_cvt_pk_bf16_f32 v9, v92, v93
	global_store_dwordx2 v[6:7], v[8:9], off offset:32
	v_cvt_pk_bf16_f32 v8, v86, v87
	v_cvt_pk_bf16_f32 v9, v88, v89
	global_store_dwordx2 v[6:7], v[8:9], off offset:64
	v_cvt_pk_bf16_f32 v8, v82, v83
	v_cvt_pk_bf16_f32 v9, v84, v85
	global_store_dwordx2 v[6:7], v[8:9], off offset:96
	v_or_b32_e32 v6, 16, v10
	v_mad_i64_i32 v[6:7], s[14:15], v6, s12, v[4:5]
	v_lshl_add_u64 v[6:7], v[6:7], 0, v[2:3]
	v_cvt_pk_bf16_f32 v8, v54, v55
	v_cvt_pk_bf16_f32 v9, v56, v57
	global_store_dwordx2 v[6:7], v[8:9], off
	v_cvt_pk_bf16_f32 v8, v42, v43
	v_cvt_pk_bf16_f32 v9, v44, v45
	global_store_dwordx2 v[6:7], v[8:9], off offset:32
	v_cvt_pk_bf16_f32 v8, v38, v39
	v_cvt_pk_bf16_f32 v9, v40, v41
	global_store_dwordx2 v[6:7], v[8:9], off offset:64
	v_cvt_pk_bf16_f32 v8, v34, v35
	v_cvt_pk_bf16_f32 v9, v36, v37
	global_store_dwordx2 v[6:7], v[8:9], off offset:96
	v_or_b32_e32 v6, 32, v10
	v_mad_i64_i32 v[6:7], s[14:15], v6, s12, v[4:5]
	v_lshl_add_u64 v[6:7], v[6:7], 0, v[2:3]
	v_cvt_pk_bf16_f32 v8, v78, v79
	v_cvt_pk_bf16_f32 v9, v80, v81
	global_store_dwordx2 v[6:7], v[8:9], off
	v_cvt_pk_bf16_f32 v8, v74, v75
	v_cvt_pk_bf16_f32 v9, v76, v77
	global_store_dwordx2 v[6:7], v[8:9], off offset:32
	v_cvt_pk_bf16_f32 v8, v70, v71
	v_cvt_pk_bf16_f32 v9, v72, v73
	global_store_dwordx2 v[6:7], v[8:9], off offset:64
	v_cvt_pk_bf16_f32 v8, v66, v67
	v_cvt_pk_bf16_f32 v9, v68, v69
	global_store_dwordx2 v[6:7], v[8:9], off offset:96
	v_or_b32_e32 v6, 48, v10
	v_mad_i64_i32 v[4:5], s[14:15], v6, s12, v[4:5]
	v_lshl_add_u64 v[2:3], v[4:5], 0, v[2:3]
	v_cvt_pk_bf16_f32 v4, v62, v63
	v_cvt_pk_bf16_f32 v5, v64, v65
	global_store_dwordx2 v[2:3], v[4:5], off
	v_cvt_pk_bf16_f32 v4, v58, v59
	v_cvt_pk_bf16_f32 v5, v60, v61
	global_store_dwordx2 v[2:3], v[4:5], off offset:32
	v_cvt_pk_bf16_f32 v4, v50, v51
	v_cvt_pk_bf16_f32 v5, v52, v53
	s_add_i32 s3, s3, s2
	global_store_dwordx2 v[2:3], v[4:5], off offset:64
	v_cvt_pk_bf16_f32 v4, v46, v47
	v_cvt_pk_bf16_f32 v5, v48, v49
	s_cmpk_lt_u32 s3, 0x280
	global_store_dwordx2 v[2:3], v[4:5], off offset:96
	s_cbranch_scc1 .LBB0_664

.Lglds2_26323:
	ds_read_b128 v[152:155], v111 offset:16384
	ds_read_b128 v[156:159], v109
	ds_read_b128 v[160:163], v111 offset:18432
	ds_read_b128 v[164:167], v111 offset:20480
	ds_read_b128 v[168:171], v112 offset:16384
	ds_read_b128 v[172:175], v109 offset:2048
	ds_read_b128 v[208:211], v109 offset:4096
	ds_read_b128 v[212:215], v110
	ds_read_b128 v[216:219], v115 offset:16384
	ds_read_b128 v[220:223], v113
	ds_read_b128 v[224:227], v115 offset:18432
	ds_read_b128 v[228:231], v115 offset:20480
	ds_read_b128 v[232:235], v116 offset:16384
	ds_read_b128 v[236:239], v113 offset:2048
	ds_read_b128 v[240:243], v113 offset:4096
	ds_read_b128 v[244:247], v114
	s_setprio 1
	s_waitcnt lgkmcnt(14)
	v_mfma_f32_16x16x32_bf16 v[92:95], v[152:155], v[156:159], v[92:95]
	s_waitcnt lgkmcnt(13)
	v_mfma_f32_16x16x32_bf16 v[88:91], v[160:163], v[156:159], v[88:91]
	s_waitcnt lgkmcnt(12)
	v_mfma_f32_16x16x32_bf16 v[84:87], v[164:167], v[156:159], v[84:87]
	s_waitcnt lgkmcnt(11)
	v_mfma_f32_16x16x32_bf16 v[80:83], v[168:171], v[156:159], v[80:83]
	s_waitcnt lgkmcnt(10)
	v_mfma_f32_16x16x32_bf16 v[76:79], v[152:155], v[172:175], v[76:79]
	v_mfma_f32_16x16x32_bf16 v[72:75], v[160:163], v[172:175], v[72:75]
	v_mfma_f32_16x16x32_bf16 v[60:63], v[164:167], v[172:175], v[60:63]
	v_mfma_f32_16x16x32_bf16 v[28:31], v[168:171], v[172:175], v[28:31]
	s_waitcnt lgkmcnt(9)
	v_mfma_f32_16x16x32_bf16 v[64:67], v[152:155], v[208:211], v[64:67]
	v_mfma_f32_16x16x32_bf16 v[36:39], v[160:163], v[208:211], v[36:39]
	v_mfma_f32_16x16x32_bf16 v[32:35], v[164:167], v[208:211], v[32:35]
	v_mfma_f32_16x16x32_bf16 v[16:19], v[168:171], v[208:211], v[16:19]
	s_waitcnt lgkmcnt(8)
	v_mfma_f32_16x16x32_bf16 v[12:15], v[152:155], v[212:215], v[12:15]
	v_mfma_f32_16x16x32_bf16 v[8:11], v[160:163], v[212:215], v[8:11]
	v_mfma_f32_16x16x32_bf16 v[4:7], v[164:167], v[212:215], v[4:7]
	v_mfma_f32_16x16x32_bf16 v[0:3], v[168:171], v[212:215], v[0:3]
	s_setprio 0
	s_waitcnt lgkmcnt(0)
	s_barrier
	s_add_i32 s4, s14, 0x80
	s_min_u32 s4, s4, 0x3c0
	s_lshl_b32 s4, s4, 1
	s_setprio 1
	v_mfma_f32_16x16x32_bf16 v[92:95], v[216:219], v[220:223], v[92:95]
	s_add_u32 m0, s15, 0x0
	v_lshl_add_u64 v[204:205], v[188:189], 0, s[4:5]
	global_load_lds_dwordx4 v[204:205], off
	v_mfma_f32_16x16x32_bf16 v[88:91], v[224:227], v[220:223], v[88:91]
	v_mfma_f32_16x16x32_bf16 v[84:87], v[228:231], v[220:223], v[84:87]
	s_add_u32 m0, s15, 0x1000
	v_lshl_add_u64 v[206:207], v[190:191], 0, s[4:5]
	global_load_lds_dwordx4 v[206:207], off
	v_mfma_f32_16x16x32_bf16 v[80:83], v[232:235], v[220:223], v[80:83]
	v_mfma_f32_16x16x32_bf16 v[76:79], v[216:219], v[236:239], v[76:79]
	s_add_u32 m0, s15, 0x2000
	v_lshl_add_u64 v[204:205], v[192:193], 0, s[4:5]
	global_load_lds_dwordx4 v[204:205], off
	v_mfma_f32_16x16x32_bf16 v[72:75], v[224:227], v[236:239], v[72:75]
	v_mfma_f32_16x16x32_bf16 v[60:63], v[228:231], v[236:239], v[60:63]
	s_add_u32 m0, s15, 0x3000
	v_lshl_add_u64 v[206:207], v[194:195], 0, s[4:5]
	global_load_lds_dwordx4 v[206:207], off
	v_mfma_f32_16x16x32_bf16 v[28:31], v[232:235], v[236:239], v[28:31]
	v_mfma_f32_16x16x32_bf16 v[64:67], v[216:219], v[240:243], v[64:67]
	s_add_u32 m0, s15, 0x4000
	v_lshl_add_u64 v[204:205], v[196:197], 0, s[4:5]
	global_load_lds_dwordx4 v[204:205], off
	v_mfma_f32_16x16x32_bf16 v[36:39], v[224:227], v[240:243], v[36:39]
	v_mfma_f32_16x16x32_bf16 v[32:35], v[228:231], v[240:243], v[32:35]
	s_add_u32 m0, s15, 0x5000
	v_lshl_add_u64 v[206:207], v[198:199], 0, s[4:5]
	global_load_lds_dwordx4 v[206:207], off
	v_mfma_f32_16x16x32_bf16 v[16:19], v[232:235], v[240:243], v[16:19]
	v_mfma_f32_16x16x32_bf16 v[12:15], v[216:219], v[244:247], v[12:15]
	s_add_u32 m0, s15, 0x6000
	v_lshl_add_u64 v[204:205], v[200:201], 0, s[4:5]
	global_load_lds_dwordx4 v[204:205], off
	v_mfma_f32_16x16x32_bf16 v[8:11], v[224:227], v[244:247], v[8:11]
	v_mfma_f32_16x16x32_bf16 v[4:7], v[228:231], v[244:247], v[4:7]
	s_add_u32 m0, s15, 0x7000
	v_lshl_add_u64 v[206:207], v[202:203], 0, s[4:5]
	global_load_lds_dwordx4 v[206:207], off
	v_mfma_f32_16x16x32_bf16 v[0:3], v[232:235], v[244:247], v[0:3]
	s_setprio 0
	s_waitcnt vmcnt(8)
	s_barrier
	ds_read_b128 v[152:155], v111 offset:49152
	ds_read_b128 v[156:159], v109 offset:32768
	ds_read_b128 v[160:163], v111 offset:51200
	ds_read_b128 v[164:167], v111 offset:53248
	ds_read_b128 v[168:171], v112 offset:49152
	ds_read_b128 v[172:175], v109 offset:34816
	ds_read_b128 v[208:211], v109 offset:36864
	ds_read_b128 v[212:215], v110 offset:32768
	ds_read_b128 v[216:219], v115 offset:49152
	ds_read_b128 v[220:223], v113 offset:32768
	ds_read_b128 v[224:227], v115 offset:51200
	ds_read_b128 v[228:231], v115 offset:53248
	ds_read_b128 v[232:235], v116 offset:49152
	ds_read_b128 v[236:239], v113 offset:34816
	ds_read_b128 v[240:243], v113 offset:36864
	ds_read_b128 v[244:247], v114 offset:32768
	s_setprio 1
	s_waitcnt lgkmcnt(14)
	v_mfma_f32_16x16x32_bf16 v[92:95], v[152:155], v[156:159], v[92:95]
	s_waitcnt lgkmcnt(13)
	v_mfma_f32_16x16x32_bf16 v[88:91], v[160:163], v[156:159], v[88:91]
	s_waitcnt lgkmcnt(12)
	v_mfma_f32_16x16x32_bf16 v[84:87], v[164:167], v[156:159], v[84:87]
	s_waitcnt lgkmcnt(11)
	v_mfma_f32_16x16x32_bf16 v[80:83], v[168:171], v[156:159], v[80:83]
	s_waitcnt lgkmcnt(10)
	v_mfma_f32_16x16x32_bf16 v[76:79], v[152:155], v[172:175], v[76:79]
	v_mfma_f32_16x16x32_bf16 v[72:75], v[160:163], v[172:175], v[72:75]
	v_mfma_f32_16x16x32_bf16 v[60:63], v[164:167], v[172:175], v[60:63]
	v_mfma_f32_16x16x32_bf16 v[28:31], v[168:171], v[172:175], v[28:31]
	s_waitcnt lgkmcnt(9)
	v_mfma_f32_16x16x32_bf16 v[64:67], v[152:155], v[208:211], v[64:67]
	v_mfma_f32_16x16x32_bf16 v[36:39], v[160:163], v[208:211], v[36:39]
	v_mfma_f32_16x16x32_bf16 v[32:35], v[164:167], v[208:211], v[32:35]
	v_mfma_f32_16x16x32_bf16 v[16:19], v[168:171], v[208:211], v[16:19]
	s_waitcnt lgkmcnt(8)
	v_mfma_f32_16x16x32_bf16 v[12:15], v[152:155], v[212:215], v[12:15]
	v_mfma_f32_16x16x32_bf16 v[8:11], v[160:163], v[212:215], v[8:11]
	v_mfma_f32_16x16x32_bf16 v[4:7], v[164:167], v[212:215], v[4:7]
	v_mfma_f32_16x16x32_bf16 v[0:3], v[168:171], v[212:215], v[0:3]
	s_setprio 0
	s_waitcnt lgkmcnt(0)
	s_barrier
	s_add_i32 s4, s14, 0xc0
	s_min_u32 s4, s4, 0x3c0
	s_lshl_b32 s4, s4, 1
	s_setprio 1
	v_mfma_f32_16x16x32_bf16 v[92:95], v[216:219], v[220:223], v[92:95]
	s_add_u32 m0, s15, 0x8000
	v_lshl_add_u64 v[204:205], v[188:189], 0, s[4:5]
	global_load_lds_dwordx4 v[204:205], off
	v_mfma_f32_16x16x32_bf16 v[88:91], v[224:227], v[220:223], v[88:91]
	v_mfma_f32_16x16x32_bf16 v[84:87], v[228:231], v[220:223], v[84:87]
	s_add_u32 m0, s15, 0x9000
	v_lshl_add_u64 v[206:207], v[190:191], 0, s[4:5]
	global_load_lds_dwordx4 v[206:207], off
	v_mfma_f32_16x16x32_bf16 v[80:83], v[232:235], v[220:223], v[80:83]
	v_mfma_f32_16x16x32_bf16 v[76:79], v[216:219], v[236:239], v[76:79]
	s_add_u32 m0, s15, 0xa000
	v_lshl_add_u64 v[204:205], v[192:193], 0, s[4:5]
	global_load_lds_dwordx4 v[204:205], off
	v_mfma_f32_16x16x32_bf16 v[72:75], v[224:227], v[236:239], v[72:75]
	v_mfma_f32_16x16x32_bf16 v[60:63], v[228:231], v[236:239], v[60:63]
	s_add_u32 m0, s15, 0xb000
	v_lshl_add_u64 v[206:207], v[194:195], 0, s[4:5]
	global_load_lds_dwordx4 v[206:207], off
	v_mfma_f32_16x16x32_bf16 v[28:31], v[232:235], v[236:239], v[28:31]
	v_mfma_f32_16x16x32_bf16 v[64:67], v[216:219], v[240:243], v[64:67]
	s_add_u32 m0, s15, 0xc000
	v_lshl_add_u64 v[204:205], v[196:197], 0, s[4:5]
	global_load_lds_dwordx4 v[204:205], off
	v_mfma_f32_16x16x32_bf16 v[36:39], v[224:227], v[240:243], v[36:39]
	v_mfma_f32_16x16x32_bf16 v[32:35], v[228:231], v[240:243], v[32:35]
	s_add_u32 m0, s15, 0xd000
	v_lshl_add_u64 v[206:207], v[198:199], 0, s[4:5]
	global_load_lds_dwordx4 v[206:207], off
	v_mfma_f32_16x16x32_bf16 v[16:19], v[232:235], v[240:243], v[16:19]
	v_mfma_f32_16x16x32_bf16 v[12:15], v[216:219], v[244:247], v[12:15]
	s_add_u32 m0, s15, 0xe000
	v_lshl_add_u64 v[204:205], v[200:201], 0, s[4:5]
	global_load_lds_dwordx4 v[204:205], off
	v_mfma_f32_16x16x32_bf16 v[8:11], v[224:227], v[244:247], v[8:11]
	v_mfma_f32_16x16x32_bf16 v[4:7], v[228:231], v[244:247], v[4:7]
	s_add_u32 m0, s15, 0xf000
	v_lshl_add_u64 v[206:207], v[202:203], 0, s[4:5]
	global_load_lds_dwordx4 v[206:207], off
	v_mfma_f32_16x16x32_bf16 v[0:3], v[232:235], v[244:247], v[0:3]
	s_setprio 0
	s_waitcnt vmcnt(8)
	s_barrier
	s_add_i32 s14, s14, 0x80
	s_add_i32 s13, s13, 2
	s_cmp_lt_u32 s13, 14
	s_cbranch_scc1 .Lglds2_26323
	s_waitcnt vmcnt(0)
	s_waitcnt vmcnt(0)
	v_or_b32_e32 v170, s12, v118
	v_add_lshl_u32 v96, v117, s11, 10
	v_readlane_b32 s12, v254, 24
	v_readlane_b32 s16, v254, 28
	v_readlane_b32 s17, v254, 29
	v_readlane_b32 s13, v254, 25
	v_readlane_b32 s14, v254, 26
	v_readlane_b32 s15, v254, 27
	v_readlane_b32 s18, v254, 30
	v_readlane_b32 s19, v254, 31
	v_readlane_b32 s20, v254, 32
	v_readlane_b32 s21, v254, 33
	v_readlane_b32 s22, v254, 34
	v_readlane_b32 s23, v254, 35
	v_readlane_b32 s24, v254, 36
	v_readlane_b32 s25, v254, 37
	v_readlane_b32 s26, v254, 38
	v_readlane_b32 s27, v254, 39
	v_lshlrev_b32_e32 v168, 2, v170
	v_mov_b32_e32 v169, v97
	v_lshlrev_b64 v[174:175], 2, v[96:97]
	v_lshl_add_u64 v[152:153], s[16:17], 0, v[174:175]
	v_lshl_add_u64 v[160:161], s[82:83], 0, v[174:175]
	v_lshl_add_u64 v[152:153], v[152:153], 0, v[168:169]
	v_lshl_add_u64 v[160:161], v[160:161], 0, v[168:169]
	global_load_dwordx4 v[120:123], v[152:153], off
	global_load_dwordx4 v[124:127], v[152:153], off offset:64
	global_load_dwordx4 v[128:131], v[152:153], off offset:128
	global_load_dwordx4 v[132:135], v[152:153], off offset:192
	v_or_b32_e32 v172, 0x4000, v96
	v_mov_b32_e32 v173, v97
	v_lshlrev_b64 v[174:175], 2, v[172:173]
	v_lshl_add_u64 v[154:155], s[16:17], 0, v[174:175]
	v_lshl_add_u64 v[162:163], s[82:83], 0, v[174:175]
	v_lshl_add_u64 v[154:155], v[154:155], 0, v[168:169]
	v_lshl_add_u64 v[162:163], v[162:163], 0, v[168:169]
	global_load_dwordx4 v[136:139], v[154:155], off
	global_load_dwordx4 v[140:143], v[154:155], off offset:64
	global_load_dwordx4 v[144:147], v[154:155], off offset:128
	global_load_dwordx4 v[148:151], v[154:155], off offset:192
	v_or_b32_e32 v172, 0x8000, v96
	v_mov_b32_e32 v173, v97
	v_lshlrev_b64 v[174:175], 2, v[172:173]
	v_lshl_add_u64 v[156:157], s[16:17], 0, v[174:175]
	v_lshl_add_u64 v[164:165], s[82:83], 0, v[174:175]
	v_lshl_add_u64 v[156:157], v[156:157], 0, v[168:169]
	v_lshl_add_u64 v[164:165], v[164:165], 0, v[168:169]
	global_load_dwordx4 v[20:23], v[156:157], off
	global_load_dwordx4 v[24:27], v[156:157], off offset:64
	global_load_dwordx4 v[40:43], v[156:157], off offset:128
	global_load_dwordx4 v[44:47], v[156:157], off offset:192
	v_or_b32_e32 v172, 0xc000, v96
	v_mov_b32_e32 v173, v97
	v_lshlrev_b64 v[174:175], 2, v[172:173]
	v_lshl_add_u64 v[158:159], s[16:17], 0, v[174:175]
	v_lshl_add_u64 v[166:167], s[82:83], 0, v[174:175]
	v_lshl_add_u64 v[158:159], v[158:159], 0, v[168:169]
	v_lshl_add_u64 v[166:167], v[166:167], 0, v[168:169]
	global_load_dwordx4 v[48:51], v[158:159], off
	global_load_dwordx4 v[52:55], v[158:159], off offset:64
	global_load_dwordx4 v[56:59], v[158:159], off offset:128
	global_load_dwordx4 v[68:71], v[158:159], off offset:192
	s_waitcnt vmcnt(15)
	v_pk_fma_f32 v[120:121], v[120:121], s[6:7], v[92:93] op_sel_hi:[1,0,1]
	v_pk_fma_f32 v[122:123], v[122:123], s[6:7], v[94:95] op_sel_hi:[1,0,1]
	s_waitcnt vmcnt(14)
	v_pk_fma_f32 v[124:125], v[124:125], s[6:7], v[88:89] op_sel_hi:[1,0,1]
	v_pk_fma_f32 v[126:127], v[126:127], s[6:7], v[90:91] op_sel_hi:[1,0,1]
	s_waitcnt vmcnt(13)
	v_pk_fma_f32 v[128:129], v[128:129], s[6:7], v[84:85] op_sel_hi:[1,0,1]
	v_pk_fma_f32 v[130:131], v[130:131], s[6:7], v[86:87] op_sel_hi:[1,0,1]
	s_waitcnt vmcnt(12)
	v_pk_fma_f32 v[132:133], v[132:133], s[6:7], v[80:81] op_sel_hi:[1,0,1]
	v_pk_fma_f32 v[134:135], v[134:135], s[6:7], v[82:83] op_sel_hi:[1,0,1]
	s_waitcnt vmcnt(11)
	v_pk_fma_f32 v[136:137], v[136:137], s[6:7], v[76:77] op_sel_hi:[1,0,1]
	v_pk_fma_f32 v[138:139], v[138:139], s[6:7], v[78:79] op_sel_hi:[1,0,1]
	s_waitcnt vmcnt(10)
	v_pk_fma_f32 v[140:141], v[140:141], s[6:7], v[72:73] op_sel_hi:[1,0,1]
	v_pk_fma_f32 v[142:143], v[142:143], s[6:7], v[74:75] op_sel_hi:[1,0,1]
	s_waitcnt vmcnt(9)
	v_pk_fma_f32 v[144:145], v[144:145], s[6:7], v[60:61] op_sel_hi:[1,0,1]
	v_pk_fma_f32 v[146:147], v[146:147], s[6:7], v[62:63] op_sel_hi:[1,0,1]
	s_waitcnt vmcnt(8)
	v_pk_fma_f32 v[148:149], v[148:149], s[6:7], v[28:29] op_sel_hi:[1,0,1]
	v_pk_fma_f32 v[150:151], v[150:151], s[6:7], v[30:31] op_sel_hi:[1,0,1]
	s_waitcnt vmcnt(7)
	v_pk_fma_f32 v[20:21], v[20:21], s[6:7], v[64:65] op_sel_hi:[1,0,1]
	v_pk_fma_f32 v[22:23], v[22:23], s[6:7], v[66:67] op_sel_hi:[1,0,1]
	s_waitcnt vmcnt(6)
	v_pk_fma_f32 v[24:25], v[24:25], s[6:7], v[36:37] op_sel_hi:[1,0,1]
	v_pk_fma_f32 v[26:27], v[26:27], s[6:7], v[38:39] op_sel_hi:[1,0,1]
	s_waitcnt vmcnt(5)
	v_pk_fma_f32 v[40:41], v[40:41], s[6:7], v[32:33] op_sel_hi:[1,0,1]
	v_pk_fma_f32 v[42:43], v[42:43], s[6:7], v[34:35] op_sel_hi:[1,0,1]
	s_waitcnt vmcnt(4)
	v_pk_fma_f32 v[44:45], v[44:45], s[6:7], v[16:17] op_sel_hi:[1,0,1]
	v_pk_fma_f32 v[46:47], v[46:47], s[6:7], v[18:19] op_sel_hi:[1,0,1]
	s_waitcnt vmcnt(3)
	v_pk_fma_f32 v[48:49], v[48:49], s[6:7], v[12:13] op_sel_hi:[1,0,1]
	v_pk_fma_f32 v[50:51], v[50:51], s[6:7], v[14:15] op_sel_hi:[1,0,1]
	s_waitcnt vmcnt(2)
	v_pk_fma_f32 v[52:53], v[52:53], s[6:7], v[8:9] op_sel_hi:[1,0,1]
	v_pk_fma_f32 v[54:55], v[54:55], s[6:7], v[10:11] op_sel_hi:[1,0,1]
	s_waitcnt vmcnt(1)
	v_pk_fma_f32 v[56:57], v[56:57], s[6:7], v[4:5] op_sel_hi:[1,0,1]
	v_pk_fma_f32 v[58:59], v[58:59], s[6:7], v[6:7] op_sel_hi:[1,0,1]
	s_waitcnt vmcnt(0)
	v_pk_fma_f32 v[68:69], v[68:69], s[6:7], v[0:1] op_sel_hi:[1,0,1]
	v_pk_fma_f32 v[70:71], v[70:71], s[6:7], v[2:3] op_sel_hi:[1,0,1]
	global_store_dwordx4 v[160:161], v[120:123], off
	global_store_dwordx4 v[160:161], v[124:127], off offset:64
	global_store_dwordx4 v[160:161], v[128:131], off offset:128
	global_store_dwordx4 v[160:161], v[132:135], off offset:192
	global_store_dwordx4 v[162:163], v[136:139], off
	global_store_dwordx4 v[162:163], v[140:143], off offset:64
	global_store_dwordx4 v[162:163], v[144:147], off offset:128
	global_store_dwordx4 v[162:163], v[148:151], off offset:192
	global_store_dwordx4 v[164:165], v[20:23], off
	global_store_dwordx4 v[164:165], v[24:27], off offset:64
	global_store_dwordx4 v[164:165], v[40:43], off offset:128
	global_store_dwordx4 v[164:165], v[44:47], off offset:192
	global_store_dwordx4 v[166:167], v[48:51], off
	global_store_dwordx4 v[166:167], v[52:55], off offset:64
	global_store_dwordx4 v[166:167], v[56:59], off offset:128
	global_store_dwordx4 v[166:167], v[68:71], off offset:192
	s_add_i32 s7, s7, s3
	s_cmpk_lt_u32 s7, 0x100
	s_cbranch_scc1 .LBB0_798

.Lglds2_28042:
	ds_read_b128 v[152:155], v111 offset:16384
	ds_read_b128 v[156:159], v109
	ds_read_b128 v[160:163], v111 offset:18432
	ds_read_b128 v[164:167], v111 offset:20480
	ds_read_b128 v[168:171], v112 offset:16384
	ds_read_b128 v[172:175], v109 offset:2048
	ds_read_b128 v[208:211], v109 offset:4096
	ds_read_b128 v[212:215], v110
	ds_read_b128 v[216:219], v115 offset:16384
	ds_read_b128 v[220:223], v113
	ds_read_b128 v[224:227], v115 offset:18432
	ds_read_b128 v[228:231], v115 offset:20480
	ds_read_b128 v[232:235], v116 offset:16384
	ds_read_b128 v[236:239], v113 offset:2048
	ds_read_b128 v[240:243], v113 offset:4096
	ds_read_b128 v[244:247], v114
	s_setprio 1
	s_waitcnt lgkmcnt(14)
	v_mfma_i32_16x16x64_i8 v[92:95], v[152:155], v[156:159], v[92:95]
	s_waitcnt lgkmcnt(13)
	v_mfma_i32_16x16x64_i8 v[88:91], v[160:163], v[156:159], v[88:91]
	s_waitcnt lgkmcnt(12)
	v_mfma_i32_16x16x64_i8 v[84:87], v[164:167], v[156:159], v[84:87]
	s_waitcnt lgkmcnt(11)
	v_mfma_i32_16x16x64_i8 v[80:83], v[168:171], v[156:159], v[80:83]
	s_waitcnt lgkmcnt(10)
	v_mfma_i32_16x16x64_i8 v[60:63], v[152:155], v[172:175], v[60:63]
	v_mfma_i32_16x16x64_i8 v[40:43], v[160:163], v[172:175], v[40:43]
	v_mfma_i32_16x16x64_i8 v[36:39], v[164:167], v[172:175], v[36:39]
	v_mfma_i32_16x16x64_i8 v[28:31], v[168:171], v[172:175], v[28:31]
	s_waitcnt lgkmcnt(9)
	v_mfma_i32_16x16x64_i8 v[32:35], v[152:155], v[208:211], v[32:35]
	v_mfma_i32_16x16x64_i8 v[24:27], v[160:163], v[208:211], v[24:27]
	v_mfma_i32_16x16x64_i8 v[20:23], v[164:167], v[208:211], v[20:23]
	v_mfma_i32_16x16x64_i8 v[16:19], v[168:171], v[208:211], v[16:19]
	s_waitcnt lgkmcnt(8)
	v_mfma_i32_16x16x64_i8 v[12:15], v[152:155], v[212:215], v[12:15]
	v_mfma_i32_16x16x64_i8 v[8:11], v[160:163], v[212:215], v[8:11]
	v_mfma_i32_16x16x64_i8 v[4:7], v[164:167], v[212:215], v[4:7]
	v_mfma_i32_16x16x64_i8 v[0:3], v[168:171], v[212:215], v[0:3]
	s_setprio 0
	s_waitcnt lgkmcnt(0)
	s_barrier
	s_add_i32 s6, s15, 0x80
	s_min_u32 s6, s6, 0x1c0
	s_lshl_b32 s6, s6, 1
	s_setprio 1
	v_mfma_i32_16x16x64_i8 v[92:95], v[216:219], v[220:223], v[92:95]
	s_add_u32 m0, s16, 0x0
	v_lshl_add_u64 v[204:205], v[188:189], 0, s[6:7]
	global_load_lds_dwordx4 v[204:205], off
	v_mfma_i32_16x16x64_i8 v[88:91], v[224:227], v[220:223], v[88:91]
	v_mfma_i32_16x16x64_i8 v[84:87], v[228:231], v[220:223], v[84:87]
	s_add_u32 m0, s16, 0x1000
	v_lshl_add_u64 v[206:207], v[190:191], 0, s[6:7]
	global_load_lds_dwordx4 v[206:207], off
	v_mfma_i32_16x16x64_i8 v[80:83], v[232:235], v[220:223], v[80:83]
	v_mfma_i32_16x16x64_i8 v[60:63], v[216:219], v[236:239], v[60:63]
	s_add_u32 m0, s16, 0x2000
	v_lshl_add_u64 v[204:205], v[192:193], 0, s[6:7]
	global_load_lds_dwordx4 v[204:205], off
	v_mfma_i32_16x16x64_i8 v[40:43], v[224:227], v[236:239], v[40:43]
	v_mfma_i32_16x16x64_i8 v[36:39], v[228:231], v[236:239], v[36:39]
	s_add_u32 m0, s16, 0x3000
	v_lshl_add_u64 v[206:207], v[194:195], 0, s[6:7]
	global_load_lds_dwordx4 v[206:207], off
	v_mfma_i32_16x16x64_i8 v[28:31], v[232:235], v[236:239], v[28:31]
	v_mfma_i32_16x16x64_i8 v[32:35], v[216:219], v[240:243], v[32:35]
	s_add_u32 m0, s16, 0x4000
	v_lshl_add_u64 v[204:205], v[196:197], 0, s[6:7]
	global_load_lds_dwordx4 v[204:205], off
	v_mfma_i32_16x16x64_i8 v[24:27], v[224:227], v[240:243], v[24:27]
	v_mfma_i32_16x16x64_i8 v[20:23], v[228:231], v[240:243], v[20:23]
	s_add_u32 m0, s16, 0x5000
	v_lshl_add_u64 v[206:207], v[198:199], 0, s[6:7]
	global_load_lds_dwordx4 v[206:207], off
	v_mfma_i32_16x16x64_i8 v[16:19], v[232:235], v[240:243], v[16:19]
	v_mfma_i32_16x16x64_i8 v[12:15], v[216:219], v[244:247], v[12:15]
	s_add_u32 m0, s16, 0x6000
	v_lshl_add_u64 v[204:205], v[200:201], 0, s[6:7]
	global_load_lds_dwordx4 v[204:205], off
	v_mfma_i32_16x16x64_i8 v[8:11], v[224:227], v[244:247], v[8:11]
	v_mfma_i32_16x16x64_i8 v[4:7], v[228:231], v[244:247], v[4:7]
	s_add_u32 m0, s16, 0x7000
	v_lshl_add_u64 v[206:207], v[202:203], 0, s[6:7]
	global_load_lds_dwordx4 v[206:207], off
	v_mfma_i32_16x16x64_i8 v[0:3], v[232:235], v[244:247], v[0:3]
	s_setprio 0
	s_waitcnt vmcnt(8)
	s_barrier
	ds_read_b128 v[152:155], v111 offset:49152
	ds_read_b128 v[156:159], v109 offset:32768
	ds_read_b128 v[160:163], v111 offset:51200
	ds_read_b128 v[164:167], v111 offset:53248
	ds_read_b128 v[168:171], v112 offset:49152
	ds_read_b128 v[172:175], v109 offset:34816
	ds_read_b128 v[208:211], v109 offset:36864
	ds_read_b128 v[212:215], v110 offset:32768
	ds_read_b128 v[216:219], v115 offset:49152
	ds_read_b128 v[220:223], v113 offset:32768
	ds_read_b128 v[224:227], v115 offset:51200
	ds_read_b128 v[228:231], v115 offset:53248
	ds_read_b128 v[232:235], v116 offset:49152
	ds_read_b128 v[236:239], v113 offset:34816
	ds_read_b128 v[240:243], v113 offset:36864
	ds_read_b128 v[244:247], v114 offset:32768
	s_setprio 1
	s_waitcnt lgkmcnt(14)
	v_mfma_i32_16x16x64_i8 v[92:95], v[152:155], v[156:159], v[92:95]
	s_waitcnt lgkmcnt(13)
	v_mfma_i32_16x16x64_i8 v[88:91], v[160:163], v[156:159], v[88:91]
	s_waitcnt lgkmcnt(12)
	v_mfma_i32_16x16x64_i8 v[84:87], v[164:167], v[156:159], v[84:87]
	s_waitcnt lgkmcnt(11)
	v_mfma_i32_16x16x64_i8 v[80:83], v[168:171], v[156:159], v[80:83]
	s_waitcnt lgkmcnt(10)
	v_mfma_i32_16x16x64_i8 v[60:63], v[152:155], v[172:175], v[60:63]
	v_mfma_i32_16x16x64_i8 v[40:43], v[160:163], v[172:175], v[40:43]
	v_mfma_i32_16x16x64_i8 v[36:39], v[164:167], v[172:175], v[36:39]
	v_mfma_i32_16x16x64_i8 v[28:31], v[168:171], v[172:175], v[28:31]
	s_waitcnt lgkmcnt(9)
	v_mfma_i32_16x16x64_i8 v[32:35], v[152:155], v[208:211], v[32:35]
	v_mfma_i32_16x16x64_i8 v[24:27], v[160:163], v[208:211], v[24:27]
	v_mfma_i32_16x16x64_i8 v[20:23], v[164:167], v[208:211], v[20:23]
	v_mfma_i32_16x16x64_i8 v[16:19], v[168:171], v[208:211], v[16:19]
	s_waitcnt lgkmcnt(8)
	v_mfma_i32_16x16x64_i8 v[12:15], v[152:155], v[212:215], v[12:15]
	v_mfma_i32_16x16x64_i8 v[8:11], v[160:163], v[212:215], v[8:11]
	v_mfma_i32_16x16x64_i8 v[4:7], v[164:167], v[212:215], v[4:7]
	v_mfma_i32_16x16x64_i8 v[0:3], v[168:171], v[212:215], v[0:3]
	s_setprio 0
	s_waitcnt lgkmcnt(0)
	s_barrier
	s_add_i32 s6, s15, 0xc0
	s_min_u32 s6, s6, 0x1c0
	s_lshl_b32 s6, s6, 1
	s_setprio 1
	v_mfma_i32_16x16x64_i8 v[92:95], v[216:219], v[220:223], v[92:95]
	s_add_u32 m0, s16, 0x8000
	v_lshl_add_u64 v[204:205], v[188:189], 0, s[6:7]
	global_load_lds_dwordx4 v[204:205], off
	v_mfma_i32_16x16x64_i8 v[88:91], v[224:227], v[220:223], v[88:91]
	v_mfma_i32_16x16x64_i8 v[84:87], v[228:231], v[220:223], v[84:87]
	s_add_u32 m0, s16, 0x9000
	v_lshl_add_u64 v[206:207], v[190:191], 0, s[6:7]
	global_load_lds_dwordx4 v[206:207], off
	v_mfma_i32_16x16x64_i8 v[80:83], v[232:235], v[220:223], v[80:83]
	v_mfma_i32_16x16x64_i8 v[60:63], v[216:219], v[236:239], v[60:63]
	s_add_u32 m0, s16, 0xa000
	v_lshl_add_u64 v[204:205], v[192:193], 0, s[6:7]
	global_load_lds_dwordx4 v[204:205], off
	v_mfma_i32_16x16x64_i8 v[40:43], v[224:227], v[236:239], v[40:43]
	v_mfma_i32_16x16x64_i8 v[36:39], v[228:231], v[236:239], v[36:39]
	s_add_u32 m0, s16, 0xb000
	v_lshl_add_u64 v[206:207], v[194:195], 0, s[6:7]
	global_load_lds_dwordx4 v[206:207], off
	v_mfma_i32_16x16x64_i8 v[28:31], v[232:235], v[236:239], v[28:31]
	v_mfma_i32_16x16x64_i8 v[32:35], v[216:219], v[240:243], v[32:35]
	s_add_u32 m0, s16, 0xc000
	v_lshl_add_u64 v[204:205], v[196:197], 0, s[6:7]
	global_load_lds_dwordx4 v[204:205], off
	v_mfma_i32_16x16x64_i8 v[24:27], v[224:227], v[240:243], v[24:27]
	v_mfma_i32_16x16x64_i8 v[20:23], v[228:231], v[240:243], v[20:23]
	s_add_u32 m0, s16, 0xd000
	v_lshl_add_u64 v[206:207], v[198:199], 0, s[6:7]
	global_load_lds_dwordx4 v[206:207], off
	v_mfma_i32_16x16x64_i8 v[16:19], v[232:235], v[240:243], v[16:19]
	v_mfma_i32_16x16x64_i8 v[12:15], v[216:219], v[244:247], v[12:15]
	s_add_u32 m0, s16, 0xe000
	v_lshl_add_u64 v[204:205], v[200:201], 0, s[6:7]
	global_load_lds_dwordx4 v[204:205], off
	v_mfma_i32_16x16x64_i8 v[8:11], v[224:227], v[244:247], v[8:11]
	v_mfma_i32_16x16x64_i8 v[4:7], v[228:231], v[244:247], v[4:7]
	s_add_u32 m0, s16, 0xf000
	v_lshl_add_u64 v[206:207], v[202:203], 0, s[6:7]
	global_load_lds_dwordx4 v[206:207], off
	v_mfma_i32_16x16x64_i8 v[0:3], v[232:235], v[244:247], v[0:3]
	s_setprio 0
	s_waitcnt vmcnt(8)
	s_barrier
	s_add_i32 s15, s15, 0x80
	s_add_i32 s14, s14, 2
	s_cmp_lt_u32 s14, 6
	s_cbranch_scc1 .Lglds2_28042
	s_waitcnt vmcnt(0)
	v_cvt_f32_i32_e32 v92, v92
	v_cvt_f32_i32_e32 v93, v93
	v_cvt_f32_i32_e32 v94, v94
	v_cvt_f32_i32_e32 v95, v95
	v_cvt_f32_i32_e32 v88, v88
	v_cvt_f32_i32_e32 v89, v89
	v_cvt_f32_i32_e32 v90, v90
	v_cvt_f32_i32_e32 v91, v91
	v_cvt_f32_i32_e32 v84, v84
	v_cvt_f32_i32_e32 v85, v85
	v_cvt_f32_i32_e32 v86, v86
	v_cvt_f32_i32_e32 v87, v87
	v_cvt_f32_i32_e32 v80, v80
	v_cvt_f32_i32_e32 v81, v81
	v_cvt_f32_i32_e32 v82, v82
	v_cvt_f32_i32_e32 v83, v83
	v_cvt_f32_i32_e32 v60, v60
	v_cvt_f32_i32_e32 v61, v61
	v_cvt_f32_i32_e32 v62, v62
	v_cvt_f32_i32_e32 v63, v63
	v_cvt_f32_i32_e32 v40, v40
	v_cvt_f32_i32_e32 v41, v41
	v_cvt_f32_i32_e32 v42, v42
	v_cvt_f32_i32_e32 v43, v43
	v_cvt_f32_i32_e32 v36, v36
	v_cvt_f32_i32_e32 v37, v37
	v_cvt_f32_i32_e32 v38, v38
	v_cvt_f32_i32_e32 v39, v39
	v_cvt_f32_i32_e32 v28, v28
	v_cvt_f32_i32_e32 v29, v29
	v_cvt_f32_i32_e32 v30, v30
	v_cvt_f32_i32_e32 v31, v31
	v_cvt_f32_i32_e32 v32, v32
	v_cvt_f32_i32_e32 v33, v33
	v_cvt_f32_i32_e32 v34, v34
	v_cvt_f32_i32_e32 v35, v35
	v_cvt_f32_i32_e32 v24, v24
	v_cvt_f32_i32_e32 v25, v25
	v_cvt_f32_i32_e32 v26, v26
	v_cvt_f32_i32_e32 v27, v27
	v_cvt_f32_i32_e32 v20, v20
	v_cvt_f32_i32_e32 v21, v21
	v_cvt_f32_i32_e32 v22, v22
	v_cvt_f32_i32_e32 v23, v23
	v_cvt_f32_i32_e32 v16, v16
	v_cvt_f32_i32_e32 v17, v17
	v_cvt_f32_i32_e32 v18, v18
	v_cvt_f32_i32_e32 v19, v19
	v_cvt_f32_i32_e32 v12, v12
	v_cvt_f32_i32_e32 v13, v13
	v_cvt_f32_i32_e32 v14, v14
	v_cvt_f32_i32_e32 v15, v15
	v_cvt_f32_i32_e32 v8, v8
	v_cvt_f32_i32_e32 v9, v9
	v_cvt_f32_i32_e32 v10, v10
	v_cvt_f32_i32_e32 v11, v11
	v_cvt_f32_i32_e32 v4, v4
	v_cvt_f32_i32_e32 v5, v5
	v_cvt_f32_i32_e32 v6, v6
	v_cvt_f32_i32_e32 v7, v7
	v_cvt_f32_i32_e32 v0, v0
	v_cvt_f32_i32_e32 v1, v1
	v_cvt_f32_i32_e32 v2, v2
	v_cvt_f32_i32_e32 v3, v3
	s_waitcnt vmcnt(0)
	v_add_u32_e32 v96, s12, v117
	v_or_b32_e32 v146, s13, v118
	v_lshl_add_u64 v[144:145], v[96:97], 2, s[68:69]
	v_lshlrev_b32_e32 v148, 2, v146
	global_load_dword v136, v[144:145], off
	global_load_dword v138, v[144:145], off offset:64
	global_load_dword v140, v[144:145], off offset:128
	global_load_dword v142, v[144:145], off offset:192
	global_load_dwordx4 v[120:123], v148, s[0:1]
	global_load_dwordx4 v[124:127], v148, s[0:1] offset:64
	global_load_dwordx4 v[128:131], v148, s[0:1] offset:128
	global_load_dwordx4 v[132:135], v148, s[0:1] offset:192
	v_lshlrev_b32_e32 v146, 1, v146
	v_mov_b32_e32 v147, v97
	v_lshlrev_b64 v[44:45], 12, v[96:97]
	v_lshl_add_u64 v[44:45], s[64:65], 0, v[44:45]
	v_lshl_add_u64 v[44:45], v[44:45], 0, v[146:147]
	v_or_b32_e32 v52, 16, v96
	v_mov_b32_e32 v53, v97
	v_lshlrev_b64 v[46:47], 12, v[52:53]
	v_lshl_add_u64 v[46:47], s[64:65], 0, v[46:47]
	v_lshl_add_u64 v[46:47], v[46:47], 0, v[146:147]
	v_or_b32_e32 v52, 32, v96
	v_mov_b32_e32 v53, v97
	v_lshlrev_b64 v[48:49], 12, v[52:53]
	v_lshl_add_u64 v[48:49], s[64:65], 0, v[48:49]
	v_lshl_add_u64 v[48:49], v[48:49], 0, v[146:147]
	v_or_b32_e32 v52, 48, v96
	v_mov_b32_e32 v53, v97
	v_lshlrev_b64 v[50:51], 12, v[52:53]
	v_lshl_add_u64 v[50:51], s[64:65], 0, v[50:51]
	v_lshl_add_u64 v[50:51], v[50:51], 0, v[146:147]
	s_waitcnt vmcnt(0)
	v_pk_mul_f32 v[92:93], v[136:137], v[92:93] op_sel_hi:[0,1]
	v_pk_mul_f32 v[94:95], v[136:137], v[94:95] op_sel_hi:[0,1]
	v_pk_mul_f32 v[92:93], v[120:121], v[92:93]
	v_pk_mul_f32 v[94:95], v[94:95], v[122:123]
	v_cvt_pk_bf16_f32 v92, v92, v93
	v_cvt_pk_bf16_f32 v93, v94, v95
	global_store_dwordx2 v[44:45], v[92:93], off
	v_pk_mul_f32 v[88:89], v[136:137], v[88:89] op_sel_hi:[0,1]
	v_pk_mul_f32 v[90:91], v[136:137], v[90:91] op_sel_hi:[0,1]
	v_pk_mul_f32 v[88:89], v[124:125], v[88:89]
	v_pk_mul_f32 v[90:91], v[90:91], v[126:127]
	v_cvt_pk_bf16_f32 v88, v88, v89
	v_cvt_pk_bf16_f32 v89, v90, v91
	global_store_dwordx2 v[44:45], v[88:89], off offset:32
	v_pk_mul_f32 v[84:85], v[136:137], v[84:85] op_sel_hi:[0,1]
	v_pk_mul_f32 v[86:87], v[136:137], v[86:87] op_sel_hi:[0,1]
	v_pk_mul_f32 v[84:85], v[128:129], v[84:85]
	v_pk_mul_f32 v[86:87], v[86:87], v[130:131]
	v_cvt_pk_bf16_f32 v84, v84, v85
	v_cvt_pk_bf16_f32 v85, v86, v87
	global_store_dwordx2 v[44:45], v[84:85], off offset:64
	v_pk_mul_f32 v[80:81], v[136:137], v[80:81] op_sel_hi:[0,1]
	v_pk_mul_f32 v[82:83], v[136:137], v[82:83] op_sel_hi:[0,1]
	v_pk_mul_f32 v[80:81], v[132:133], v[80:81]
	v_pk_mul_f32 v[82:83], v[82:83], v[134:135]
	v_cvt_pk_bf16_f32 v80, v80, v81
	v_cvt_pk_bf16_f32 v81, v82, v83
	global_store_dwordx2 v[44:45], v[80:81], off offset:96
	v_pk_mul_f32 v[60:61], v[138:139], v[60:61] op_sel_hi:[0,1]
	v_pk_mul_f32 v[62:63], v[138:139], v[62:63] op_sel_hi:[0,1]
	v_pk_mul_f32 v[60:61], v[120:121], v[60:61]
	v_pk_mul_f32 v[62:63], v[62:63], v[122:123]
	v_cvt_pk_bf16_f32 v60, v60, v61
	v_cvt_pk_bf16_f32 v61, v62, v63
	global_store_dwordx2 v[46:47], v[60:61], off
	v_pk_mul_f32 v[40:41], v[138:139], v[40:41] op_sel_hi:[0,1]
	v_pk_mul_f32 v[42:43], v[138:139], v[42:43] op_sel_hi:[0,1]
	v_pk_mul_f32 v[40:41], v[124:125], v[40:41]
	v_pk_mul_f32 v[42:43], v[42:43], v[126:127]
	v_cvt_pk_bf16_f32 v40, v40, v41
	v_cvt_pk_bf16_f32 v41, v42, v43
	global_store_dwordx2 v[46:47], v[40:41], off offset:32
	v_pk_mul_f32 v[36:37], v[138:139], v[36:37] op_sel_hi:[0,1]
	v_pk_mul_f32 v[38:39], v[138:139], v[38:39] op_sel_hi:[0,1]
	v_pk_mul_f32 v[36:37], v[128:129], v[36:37]
	v_pk_mul_f32 v[38:39], v[38:39], v[130:131]
	v_cvt_pk_bf16_f32 v36, v36, v37
	v_cvt_pk_bf16_f32 v37, v38, v39
	global_store_dwordx2 v[46:47], v[36:37], off offset:64
	v_pk_mul_f32 v[28:29], v[138:139], v[28:29] op_sel_hi:[0,1]
	v_pk_mul_f32 v[30:31], v[138:139], v[30:31] op_sel_hi:[0,1]
	v_pk_mul_f32 v[28:29], v[132:133], v[28:29]
	v_pk_mul_f32 v[30:31], v[30:31], v[134:135]
	v_cvt_pk_bf16_f32 v28, v28, v29
	v_cvt_pk_bf16_f32 v29, v30, v31
	global_store_dwordx2 v[46:47], v[28:29], off offset:96
	v_pk_mul_f32 v[32:33], v[140:141], v[32:33] op_sel_hi:[0,1]
	v_pk_mul_f32 v[34:35], v[140:141], v[34:35] op_sel_hi:[0,1]
	v_pk_mul_f32 v[32:33], v[120:121], v[32:33]
	v_pk_mul_f32 v[34:35], v[34:35], v[122:123]
	v_cvt_pk_bf16_f32 v32, v32, v33
	v_cvt_pk_bf16_f32 v33, v34, v35
	global_store_dwordx2 v[48:49], v[32:33], off
	v_pk_mul_f32 v[24:25], v[140:141], v[24:25] op_sel_hi:[0,1]
	v_pk_mul_f32 v[26:27], v[140:141], v[26:27] op_sel_hi:[0,1]
	v_pk_mul_f32 v[24:25], v[124:125], v[24:25]
	v_pk_mul_f32 v[26:27], v[26:27], v[126:127]
	v_cvt_pk_bf16_f32 v24, v24, v25
	v_cvt_pk_bf16_f32 v25, v26, v27
	global_store_dwordx2 v[48:49], v[24:25], off offset:32
	v_pk_mul_f32 v[20:21], v[140:141], v[20:21] op_sel_hi:[0,1]
	v_pk_mul_f32 v[22:23], v[140:141], v[22:23] op_sel_hi:[0,1]
	v_pk_mul_f32 v[20:21], v[128:129], v[20:21]
	v_pk_mul_f32 v[22:23], v[22:23], v[130:131]
	v_cvt_pk_bf16_f32 v20, v20, v21
	v_cvt_pk_bf16_f32 v21, v22, v23
	global_store_dwordx2 v[48:49], v[20:21], off offset:64
	v_pk_mul_f32 v[16:17], v[140:141], v[16:17] op_sel_hi:[0,1]
	v_pk_mul_f32 v[18:19], v[140:141], v[18:19] op_sel_hi:[0,1]
	v_pk_mul_f32 v[16:17], v[132:133], v[16:17]
	v_pk_mul_f32 v[18:19], v[18:19], v[134:135]
	v_cvt_pk_bf16_f32 v16, v16, v17
	v_cvt_pk_bf16_f32 v17, v18, v19
	global_store_dwordx2 v[48:49], v[16:17], off offset:96
	v_pk_mul_f32 v[12:13], v[142:143], v[12:13] op_sel_hi:[0,1]
	v_pk_mul_f32 v[14:15], v[142:143], v[14:15] op_sel_hi:[0,1]
	v_pk_mul_f32 v[12:13], v[120:121], v[12:13]
	v_pk_mul_f32 v[14:15], v[14:15], v[122:123]
	v_cvt_pk_bf16_f32 v12, v12, v13
	v_cvt_pk_bf16_f32 v13, v14, v15
	global_store_dwordx2 v[50:51], v[12:13], off
	v_pk_mul_f32 v[8:9], v[142:143], v[8:9] op_sel_hi:[0,1]
	v_pk_mul_f32 v[10:11], v[142:143], v[10:11] op_sel_hi:[0,1]
	v_pk_mul_f32 v[8:9], v[124:125], v[8:9]
	v_pk_mul_f32 v[10:11], v[10:11], v[126:127]
	v_cvt_pk_bf16_f32 v8, v8, v9
	v_cvt_pk_bf16_f32 v9, v10, v11
	global_store_dwordx2 v[50:51], v[8:9], off offset:32
	v_pk_mul_f32 v[4:5], v[142:143], v[4:5] op_sel_hi:[0,1]
	v_pk_mul_f32 v[6:7], v[142:143], v[6:7] op_sel_hi:[0,1]
	v_pk_mul_f32 v[4:5], v[128:129], v[4:5]
	v_pk_mul_f32 v[6:7], v[6:7], v[130:131]
	v_cvt_pk_bf16_f32 v4, v4, v5
	v_cvt_pk_bf16_f32 v5, v6, v7
	global_store_dwordx2 v[50:51], v[4:5], off offset:64
	v_pk_mul_f32 v[0:1], v[142:143], v[0:1] op_sel_hi:[0,1]
	v_pk_mul_f32 v[2:3], v[142:143], v[2:3] op_sel_hi:[0,1]
	v_pk_mul_f32 v[0:1], v[132:133], v[0:1]
	v_pk_mul_f32 v[2:3], v[2:3], v[134:135]
	v_cvt_pk_bf16_f32 v0, v0, v1
	v_cvt_pk_bf16_f32 v1, v2, v3
	global_store_dwordx2 v[50:51], v[0:1], off offset:96
	s_add_i32 s8, s8, s3
	s_cmpk_lt_u32 s8, 0x200
	s_cbranch_scc1 .LBB0_889
